# v66 + K-loop rotation: the next iteration's first 8 fragment reads are issued right behind the closing barrier, before the loop-edge scalar work (6 K-loops)
# baseline (speedup 1.0000x reference)
.Lkrot_162:
	s_add_u32 s58, s40, 0xfff00080
	s_addc_u32 s59, s41, -1
	s_cmp_eq_u32 s73, 60
	s_cselect_b32 s63, s25, s59
	s_cselect_b32 s62, s67, s58
	s_cselect_b32 s59, s23, s72
	s_cselect_b32 s58, s70, s71
	v_lshl_add_u64 v[146:147], s[40:41], 0, v[138:139]
	s_add_i32 m0, s42, 0xc000
	ds_read_b128 v[186:189], v153
	ds_read_b128 v[190:193], v153 offset:1024
	ds_read_b128 v[194:197], v153 offset:2048
	ds_read_b128 v[198:201], v153 offset:3072
	ds_read_b128 v[202:205], v153 offset:4096
	ds_read_b128 v[206:209], v153 offset:5120
	ds_read_b128 v[210:213], v153 offset:6144
	ds_read_b128 v[214:217], v153 offset:7168
	global_load_lds_dwordx4 v[146:147], off
	v_lshl_add_u64 v[146:147], s[40:41], 0, v[140:141]
	s_add_i32 m0, s42, 0xe000
	s_nop 0
	global_load_lds_dwordx4 v[146:147], off
	s_waitcnt vmcnt(8)
	s_waitcnt lgkmcnt(0)
	s_barrier
	s_setprio 1
	s_waitcnt lgkmcnt(0)
	v_mfma_f32_16x16x32_bf16 v[126:129], v[154:157], v[186:189], v[126:129]
	v_mfma_f32_16x16x32_bf16 v[118:121], v[162:165], v[186:189], v[118:121]
	v_mfma_f32_16x16x32_bf16 v[110:113], v[154:157], v[194:197], v[110:113]
	v_mfma_f32_16x16x32_bf16 v[102:105], v[162:165], v[194:197], v[102:105]
	v_mfma_f32_16x16x32_bf16 v[94:97], v[154:157], v[202:205], v[94:97]
	v_mfma_f32_16x16x32_bf16 v[86:89], v[162:165], v[202:205], v[86:89]
	v_mfma_f32_16x16x32_bf16 v[78:81], v[154:157], v[210:213], v[78:81]
	v_mfma_f32_16x16x32_bf16 v[70:73], v[162:165], v[210:213], v[70:73]
	v_mfma_f32_16x16x32_bf16 v[126:129], v[158:161], v[190:193], v[126:129]
	v_mfma_f32_16x16x32_bf16 v[118:121], v[166:169], v[190:193], v[118:121]
	v_mfma_f32_16x16x32_bf16 v[110:113], v[158:161], v[198:201], v[110:113]
	v_mfma_f32_16x16x32_bf16 v[102:105], v[166:169], v[198:201], v[102:105]
	v_mfma_f32_16x16x32_bf16 v[94:97], v[158:161], v[206:209], v[94:97]
	v_mfma_f32_16x16x32_bf16 v[86:89], v[166:169], v[206:209], v[86:89]
	v_mfma_f32_16x16x32_bf16 v[78:81], v[158:161], v[214:217], v[78:81]
	v_mfma_f32_16x16x32_bf16 v[70:73], v[166:169], v[214:217], v[70:73]
	s_setprio 0
	s_setprio 1
	v_mfma_f32_16x16x32_bf16 v[122:125], v[170:173], v[186:189], v[122:125]
	v_mfma_f32_16x16x32_bf16 v[114:117], v[178:181], v[186:189], v[114:117]
	v_mfma_f32_16x16x32_bf16 v[106:109], v[170:173], v[194:197], v[106:109]
	v_mfma_f32_16x16x32_bf16 v[98:101], v[178:181], v[194:197], v[98:101]
	v_mfma_f32_16x16x32_bf16 v[90:93], v[170:173], v[202:205], v[90:93]
	v_mfma_f32_16x16x32_bf16 v[82:85], v[178:181], v[202:205], v[82:85]
	v_mfma_f32_16x16x32_bf16 v[74:77], v[170:173], v[210:213], v[74:77]
	v_mfma_f32_16x16x32_bf16 v[66:69], v[178:181], v[210:213], v[66:69]
	v_mfma_f32_16x16x32_bf16 v[122:125], v[174:177], v[190:193], v[122:125]
	v_mfma_f32_16x16x32_bf16 v[114:117], v[182:185], v[190:193], v[114:117]
	v_mfma_f32_16x16x32_bf16 v[106:109], v[174:177], v[198:201], v[106:109]
	v_mfma_f32_16x16x32_bf16 v[98:101], v[182:185], v[198:201], v[98:101]
	v_mfma_f32_16x16x32_bf16 v[90:93], v[174:177], v[206:209], v[90:93]
	v_mfma_f32_16x16x32_bf16 v[82:85], v[182:185], v[206:209], v[82:85]
	v_mfma_f32_16x16x32_bf16 v[74:77], v[174:177], v[214:217], v[74:77]
	v_mfma_f32_16x16x32_bf16 v[66:69], v[182:185], v[214:217], v[66:69]
	s_setprio 0
	s_barrier
	s_add_i32 s74, s50, s15
	v_lshl_add_u64 v[146:147], s[58:59], 0, v[134:135]
	s_mov_b32 m0, s74
	ds_read_b128 v[186:189], v153 offset:16384
	ds_read_b128 v[190:193], v153 offset:17408
	ds_read_b128 v[194:197], v153 offset:18432
	ds_read_b128 v[198:201], v153 offset:19456
	ds_read_b128 v[202:205], v153 offset:20480
	ds_read_b128 v[206:209], v153 offset:21504
	ds_read_b128 v[210:213], v153 offset:22528
	ds_read_b128 v[214:217], v153 offset:23552
	global_load_lds_dwordx4 v[146:147], off
	s_add_i32 m0, s74, 0x2000
	s_add_u32 s74, s58, 0x100000
	v_lshl_add_u64 v[218:219], s[58:59], 0, v[130:131]
	s_addc_u32 s75, s59, 0
	s_add_i32 s82, s51, s15
	global_load_lds_dwordx4 v[218:219], off
	v_lshl_add_u64 v[220:221], s[74:75], 0, v[134:135]
	s_mov_b32 m0, s82
	v_lshl_add_u64 v[222:223], s[62:63], 0, v[132:133]
	global_load_lds_dwordx4 v[220:221], off
	v_lshl_add_u64 v[220:221], s[74:75], 0, v[130:131]
	s_add_i32 m0, s82, 0x2000
	s_nop 0
	global_load_lds_dwordx4 v[220:221], off
	v_lshl_add_u64 v[220:221], s[62:63], 0, v[136:137]
	s_mov_b32 m0, s42
	s_nop 0
	global_load_lds_dwordx4 v[220:221], off
	s_mov_b32 m0, s43
	s_nop 0
	global_load_lds_dwordx4 v[222:223], off
	s_waitcnt vmcnt(8)
	s_waitcnt lgkmcnt(0)
	s_barrier
	s_setprio 1
	s_waitcnt lgkmcnt(0)
	v_mfma_f32_16x16x32_bf16 v[62:65], v[154:157], v[186:189], v[62:65]
	v_mfma_f32_16x16x32_bf16 v[54:57], v[162:165], v[186:189], v[54:57]
	v_mfma_f32_16x16x32_bf16 v[46:49], v[154:157], v[194:197], v[46:49]
	v_mfma_f32_16x16x32_bf16 v[38:41], v[162:165], v[194:197], v[38:41]
	v_mfma_f32_16x16x32_bf16 v[30:33], v[154:157], v[202:205], v[30:33]
	v_mfma_f32_16x16x32_bf16 v[22:25], v[162:165], v[202:205], v[22:25]
	v_mfma_f32_16x16x32_bf16 v[14:17], v[154:157], v[210:213], v[14:17]
	v_mfma_f32_16x16x32_bf16 v[6:9], v[162:165], v[210:213], v[6:9]
	v_mfma_f32_16x16x32_bf16 v[62:65], v[158:161], v[190:193], v[62:65]
	v_mfma_f32_16x16x32_bf16 v[54:57], v[166:169], v[190:193], v[54:57]
	v_mfma_f32_16x16x32_bf16 v[46:49], v[158:161], v[198:201], v[46:49]
	v_mfma_f32_16x16x32_bf16 v[38:41], v[166:169], v[198:201], v[38:41]
	v_mfma_f32_16x16x32_bf16 v[30:33], v[158:161], v[206:209], v[30:33]
	v_mfma_f32_16x16x32_bf16 v[22:25], v[166:169], v[206:209], v[22:25]
	v_mfma_f32_16x16x32_bf16 v[14:17], v[158:161], v[214:217], v[14:17]
	v_mfma_f32_16x16x32_bf16 v[6:9], v[166:169], v[214:217], v[6:9]
	s_setprio 0
	s_setprio 1
	v_mfma_f32_16x16x32_bf16 v[58:61], v[170:173], v[186:189], v[58:61]
	v_mfma_f32_16x16x32_bf16 v[50:53], v[178:181], v[186:189], v[50:53]
	v_mfma_f32_16x16x32_bf16 v[42:45], v[170:173], v[194:197], v[42:45]
	v_mfma_f32_16x16x32_bf16 v[34:37], v[178:181], v[194:197], v[34:37]
	v_mfma_f32_16x16x32_bf16 v[26:29], v[170:173], v[202:205], v[26:29]
	v_mfma_f32_16x16x32_bf16 v[18:21], v[178:181], v[202:205], v[18:21]
	v_mfma_f32_16x16x32_bf16 v[10:13], v[170:173], v[210:213], v[10:13]
	v_mfma_f32_16x16x32_bf16 v[2:5], v[178:181], v[210:213], v[2:5]
	v_mfma_f32_16x16x32_bf16 v[58:61], v[174:177], v[190:193], v[58:61]
	v_mfma_f32_16x16x32_bf16 v[50:53], v[182:185], v[190:193], v[50:53]
	v_mfma_f32_16x16x32_bf16 v[42:45], v[174:177], v[198:201], v[42:45]
	v_mfma_f32_16x16x32_bf16 v[34:37], v[182:185], v[198:201], v[34:37]
	v_mfma_f32_16x16x32_bf16 v[26:29], v[174:177], v[206:209], v[26:29]
	v_mfma_f32_16x16x32_bf16 v[18:21], v[182:185], v[206:209], v[18:21]
	v_mfma_f32_16x16x32_bf16 v[10:13], v[174:177], v[214:217], v[10:13]
	v_mfma_f32_16x16x32_bf16 v[2:5], v[182:185], v[214:217], v[2:5]
	s_setprio 0
	s_barrier
	s_add_i32 s74, 0, 0x18000
	s_add_i32 s75, 0, 0x1c000
	v_add_u32_e32 v166, s74, v149
	v_add_u32_e32 v182, s75, v149
	ds_read_b128 v[154:157], v166
	ds_read_b128 v[158:161], v166 offset:1024
	ds_read_b128 v[162:165], v166 offset:2048
	ds_read_b128 v[166:169], v166 offset:3072
	ds_read_b128 v[170:173], v182
	ds_read_b128 v[174:177], v182 offset:1024
	ds_read_b128 v[178:181], v182 offset:2048
	ds_read_b128 v[182:185], v182 offset:3072
	s_add_u32 s62, s62, 0x100000
	s_addc_u32 s63, s63, 0
	s_mov_b32 m0, s44
	v_lshl_add_u64 v[224:225], s[62:63], 0, v[136:137]
	ds_read_b128 v[186:189], v153 offset:32768
	ds_read_b128 v[190:193], v153 offset:33792
	ds_read_b128 v[194:197], v153 offset:34816
	ds_read_b128 v[198:201], v153 offset:35840
	ds_read_b128 v[202:205], v153 offset:36864
	ds_read_b128 v[206:209], v153 offset:37888
	ds_read_b128 v[210:213], v153 offset:38912
	ds_read_b128 v[214:217], v153 offset:39936
	global_load_lds_dwordx4 v[224:225], off
	v_lshl_add_u64 v[224:225], s[62:63], 0, v[132:133]
	s_mov_b32 m0, s45
	s_nop 0
	global_load_lds_dwordx4 v[224:225], off
	s_waitcnt vmcnt(8)
	s_waitcnt lgkmcnt(0)
	s_barrier
	s_setprio 1
	s_waitcnt lgkmcnt(0)
	v_mfma_f32_16x16x32_bf16 v[126:129], v[154:157], v[186:189], v[126:129]
	v_mfma_f32_16x16x32_bf16 v[118:121], v[162:165], v[186:189], v[118:121]
	v_mfma_f32_16x16x32_bf16 v[110:113], v[154:157], v[194:197], v[110:113]
	v_mfma_f32_16x16x32_bf16 v[102:105], v[162:165], v[194:197], v[102:105]
	v_mfma_f32_16x16x32_bf16 v[94:97], v[154:157], v[202:205], v[94:97]
	v_mfma_f32_16x16x32_bf16 v[86:89], v[162:165], v[202:205], v[86:89]
	v_mfma_f32_16x16x32_bf16 v[78:81], v[154:157], v[210:213], v[78:81]
	v_mfma_f32_16x16x32_bf16 v[70:73], v[162:165], v[210:213], v[70:73]
	v_mfma_f32_16x16x32_bf16 v[126:129], v[158:161], v[190:193], v[126:129]
	v_mfma_f32_16x16x32_bf16 v[118:121], v[166:169], v[190:193], v[118:121]
	v_mfma_f32_16x16x32_bf16 v[110:113], v[158:161], v[198:201], v[110:113]
	v_mfma_f32_16x16x32_bf16 v[102:105], v[166:169], v[198:201], v[102:105]
	v_mfma_f32_16x16x32_bf16 v[94:97], v[158:161], v[206:209], v[94:97]
	v_mfma_f32_16x16x32_bf16 v[86:89], v[166:169], v[206:209], v[86:89]
	v_mfma_f32_16x16x32_bf16 v[78:81], v[158:161], v[214:217], v[78:81]
	v_mfma_f32_16x16x32_bf16 v[70:73], v[166:169], v[214:217], v[70:73]
	s_setprio 0
	s_setprio 1
	v_mfma_f32_16x16x32_bf16 v[122:125], v[170:173], v[186:189], v[122:125]
	v_mfma_f32_16x16x32_bf16 v[114:117], v[178:181], v[186:189], v[114:117]
	v_mfma_f32_16x16x32_bf16 v[106:109], v[170:173], v[194:197], v[106:109]
	v_mfma_f32_16x16x32_bf16 v[98:101], v[178:181], v[194:197], v[98:101]
	v_mfma_f32_16x16x32_bf16 v[90:93], v[170:173], v[202:205], v[90:93]
	v_mfma_f32_16x16x32_bf16 v[82:85], v[178:181], v[202:205], v[82:85]
	v_mfma_f32_16x16x32_bf16 v[74:77], v[170:173], v[210:213], v[74:77]
	v_mfma_f32_16x16x32_bf16 v[66:69], v[178:181], v[210:213], v[66:69]
	v_mfma_f32_16x16x32_bf16 v[122:125], v[174:177], v[190:193], v[122:125]
	v_mfma_f32_16x16x32_bf16 v[114:117], v[182:185], v[190:193], v[114:117]
	v_mfma_f32_16x16x32_bf16 v[106:109], v[174:177], v[198:201], v[106:109]
	v_mfma_f32_16x16x32_bf16 v[98:101], v[182:185], v[198:201], v[98:101]
	v_mfma_f32_16x16x32_bf16 v[90:93], v[174:177], v[206:209], v[90:93]
	v_mfma_f32_16x16x32_bf16 v[82:85], v[182:185], v[206:209], v[82:85]
	v_mfma_f32_16x16x32_bf16 v[74:77], v[174:177], v[214:217], v[74:77]
	v_mfma_f32_16x16x32_bf16 v[66:69], v[182:185], v[214:217], v[66:69]
	s_setprio 0
	s_barrier
	s_add_i32 s62, s74, s15
	v_lshl_add_u64 v[146:147], v[146:147], 0, s[10:11]
	s_mov_b32 m0, s62
	ds_read_b128 v[186:189], v153 offset:49152
	ds_read_b128 v[190:193], v153 offset:50176
	ds_read_b128 v[194:197], v153 offset:51200
	ds_read_b128 v[198:201], v153 offset:52224
	ds_read_b128 v[202:205], v153 offset:53248
	ds_read_b128 v[206:209], v153 offset:54272
	ds_read_b128 v[210:213], v153 offset:55296
	ds_read_b128 v[214:217], v153 offset:56320
	global_load_lds_dwordx4 v[146:147], off
	s_add_i32 m0, s62, 0x2000
	s_add_u32 s58, s58, 0x100080
	v_lshl_add_u64 v[146:147], v[218:219], 0, s[10:11]
	s_addc_u32 s59, s59, 0
	s_add_i32 s62, s75, s15
	global_load_lds_dwordx4 v[146:147], off
	v_lshl_add_u64 v[146:147], s[58:59], 0, v[134:135]
	s_mov_b32 m0, s62
	s_nop 0
	global_load_lds_dwordx4 v[146:147], off
	v_lshl_add_u64 v[146:147], s[58:59], 0, v[130:131]
	s_add_i32 m0, s62, 0x2000
	s_nop 0
	global_load_lds_dwordx4 v[146:147], off
	v_lshl_add_u64 v[146:147], v[220:221], 0, s[10:11]
	s_mov_b32 m0, s47
	s_nop 0
	global_load_lds_dwordx4 v[146:147], off
	v_lshl_add_u64 v[146:147], v[222:223], 0, s[10:11]
	s_mov_b32 m0, s48
	s_nop 0
	global_load_lds_dwordx4 v[146:147], off
	s_waitcnt vmcnt(8)
	s_waitcnt lgkmcnt(0)
	s_barrier
	s_setprio 1
	s_waitcnt lgkmcnt(0)
	v_mfma_f32_16x16x32_bf16 v[62:65], v[154:157], v[186:189], v[62:65]
	v_mfma_f32_16x16x32_bf16 v[54:57], v[162:165], v[186:189], v[54:57]
	v_mfma_f32_16x16x32_bf16 v[46:49], v[154:157], v[194:197], v[46:49]
	v_mfma_f32_16x16x32_bf16 v[38:41], v[162:165], v[194:197], v[38:41]
	v_mfma_f32_16x16x32_bf16 v[30:33], v[154:157], v[202:205], v[30:33]
	v_mfma_f32_16x16x32_bf16 v[22:25], v[162:165], v[202:205], v[22:25]
	v_mfma_f32_16x16x32_bf16 v[14:17], v[154:157], v[210:213], v[14:17]
	v_mfma_f32_16x16x32_bf16 v[6:9], v[162:165], v[210:213], v[6:9]
	v_mfma_f32_16x16x32_bf16 v[62:65], v[158:161], v[190:193], v[62:65]
	v_mfma_f32_16x16x32_bf16 v[54:57], v[166:169], v[190:193], v[54:57]
	v_mfma_f32_16x16x32_bf16 v[46:49], v[158:161], v[198:201], v[46:49]
	v_mfma_f32_16x16x32_bf16 v[38:41], v[166:169], v[198:201], v[38:41]
	v_mfma_f32_16x16x32_bf16 v[30:33], v[158:161], v[206:209], v[30:33]
	v_mfma_f32_16x16x32_bf16 v[22:25], v[166:169], v[206:209], v[22:25]
	v_mfma_f32_16x16x32_bf16 v[14:17], v[158:161], v[214:217], v[14:17]
	v_mfma_f32_16x16x32_bf16 v[6:9], v[166:169], v[214:217], v[6:9]
	s_setprio 0
	s_setprio 1
	v_mfma_f32_16x16x32_bf16 v[58:61], v[170:173], v[186:189], v[58:61]
	v_mfma_f32_16x16x32_bf16 v[50:53], v[178:181], v[186:189], v[50:53]
	v_mfma_f32_16x16x32_bf16 v[42:45], v[170:173], v[194:197], v[42:45]
	v_mfma_f32_16x16x32_bf16 v[34:37], v[178:181], v[194:197], v[34:37]
	v_mfma_f32_16x16x32_bf16 v[26:29], v[170:173], v[202:205], v[26:29]
	v_mfma_f32_16x16x32_bf16 v[18:21], v[178:181], v[202:205], v[18:21]
	v_mfma_f32_16x16x32_bf16 v[10:13], v[170:173], v[210:213], v[10:13]
	v_mfma_f32_16x16x32_bf16 v[2:5], v[178:181], v[210:213], v[2:5]
	v_mfma_f32_16x16x32_bf16 v[58:61], v[174:177], v[190:193], v[58:61]
	v_mfma_f32_16x16x32_bf16 v[50:53], v[182:185], v[190:193], v[50:53]
	v_mfma_f32_16x16x32_bf16 v[42:45], v[174:177], v[198:201], v[42:45]
	v_mfma_f32_16x16x32_bf16 v[34:37], v[182:185], v[198:201], v[34:37]
	v_mfma_f32_16x16x32_bf16 v[26:29], v[174:177], v[206:209], v[26:29]
	v_mfma_f32_16x16x32_bf16 v[18:21], v[182:185], v[206:209], v[18:21]
	v_mfma_f32_16x16x32_bf16 v[10:13], v[174:177], v[214:217], v[10:13]
	v_mfma_f32_16x16x32_bf16 v[2:5], v[182:185], v[214:217], v[2:5]
	s_setprio 0
	s_barrier
	ds_read_b128 v[154:157], v151
	ds_read_b128 v[158:161], v151 offset:1024
	ds_read_b128 v[162:165], v151 offset:2048
	ds_read_b128 v[166:169], v151 offset:3072
	ds_read_b128 v[170:173], v152
	ds_read_b128 v[174:177], v152 offset:1024
	ds_read_b128 v[178:181], v152 offset:2048
	ds_read_b128 v[182:185], v152 offset:3072
	s_add_i32 s73, s73, 2
	s_add_u32 s40, s40, 0x100
	s_addc_u32 s41, s41, 0
	s_add_u32 s71, s71, 0x100
	s_addc_u32 s72, s72, 0
	s_cmp_gt_u32 s73, 61
	s_cbranch_scc0 .Lkrot_162
	s_waitcnt lgkmcnt(0)
	s_and_b64 vcc, exec, s[12:13]
	s_cbranch_vccz .LBB0_165
	s_barrier

.Lkrot_260:
	s_add_u32 s30, s28, 0x100
	s_addc_u32 s31, s29, 0
	s_cmpk_eq_i32 s74, 0xa8
	s_cselect_b32 s63, s5, s31
	s_cselect_b32 s62, s4, s30
	s_cselect_b32 s41, s27, s73
	s_cselect_b32 s40, s26, s72
	v_lshl_add_u64 v[146:147], s[28:29], 0, v[138:139]
	s_add_i32 m0, s15, 0xc000
	ds_read_b128 v[186:189], v152
	ds_read_b128 v[190:193], v152 offset:1024
	ds_read_b128 v[194:197], v152 offset:2048
	ds_read_b128 v[198:201], v152 offset:3072
	ds_read_b128 v[202:205], v152 offset:4096
	ds_read_b128 v[206:209], v152 offset:5120
	ds_read_b128 v[210:213], v152 offset:6144
	ds_read_b128 v[214:217], v152 offset:7168
	global_load_lds_dwordx4 v[146:147], off
	v_lshl_add_u64 v[146:147], s[28:29], 0, v[140:141]
	s_add_i32 m0, s15, 0xe000
	s_nop 0
	global_load_lds_dwordx4 v[146:147], off
	s_waitcnt vmcnt(8)
	s_waitcnt lgkmcnt(0)
	s_barrier
	s_setprio 1
	s_waitcnt lgkmcnt(0)
	v_mfma_f32_16x16x32_bf16 v[126:129], v[154:157], v[186:189], v[126:129]
	v_mfma_f32_16x16x32_bf16 v[122:125], v[162:165], v[186:189], v[122:125]
	v_mfma_f32_16x16x32_bf16 v[118:121], v[154:157], v[194:197], v[118:121]
	v_mfma_f32_16x16x32_bf16 v[110:113], v[162:165], v[194:197], v[110:113]
	v_mfma_f32_16x16x32_bf16 v[102:105], v[154:157], v[202:205], v[102:105]
	v_mfma_f32_16x16x32_bf16 v[94:97], v[162:165], v[202:205], v[94:97]
	v_mfma_f32_16x16x32_bf16 v[82:85], v[154:157], v[210:213], v[82:85]
	v_mfma_f32_16x16x32_bf16 v[74:77], v[162:165], v[210:213], v[74:77]
	v_mfma_f32_16x16x32_bf16 v[126:129], v[158:161], v[190:193], v[126:129]
	v_mfma_f32_16x16x32_bf16 v[122:125], v[166:169], v[190:193], v[122:125]
	v_mfma_f32_16x16x32_bf16 v[118:121], v[158:161], v[198:201], v[118:121]
	v_mfma_f32_16x16x32_bf16 v[110:113], v[166:169], v[198:201], v[110:113]
	v_mfma_f32_16x16x32_bf16 v[102:105], v[158:161], v[206:209], v[102:105]
	v_mfma_f32_16x16x32_bf16 v[94:97], v[166:169], v[206:209], v[94:97]
	v_mfma_f32_16x16x32_bf16 v[82:85], v[158:161], v[214:217], v[82:85]
	v_mfma_f32_16x16x32_bf16 v[74:77], v[166:169], v[214:217], v[74:77]
	s_setprio 0
	s_setprio 1
	v_mfma_f32_16x16x32_bf16 v[114:117], v[170:173], v[186:189], v[114:117]
	v_mfma_f32_16x16x32_bf16 v[106:109], v[178:181], v[186:189], v[106:109]
	v_mfma_f32_16x16x32_bf16 v[98:101], v[170:173], v[194:197], v[98:101]
	v_mfma_f32_16x16x32_bf16 v[90:93], v[178:181], v[194:197], v[90:93]
	v_mfma_f32_16x16x32_bf16 v[86:89], v[170:173], v[202:205], v[86:89]
	v_mfma_f32_16x16x32_bf16 v[78:81], v[178:181], v[202:205], v[78:81]
	v_mfma_f32_16x16x32_bf16 v[70:73], v[170:173], v[210:213], v[70:73]
	v_mfma_f32_16x16x32_bf16 v[66:69], v[178:181], v[210:213], v[66:69]
	v_mfma_f32_16x16x32_bf16 v[114:117], v[174:177], v[190:193], v[114:117]
	v_mfma_f32_16x16x32_bf16 v[106:109], v[182:185], v[190:193], v[106:109]
	v_mfma_f32_16x16x32_bf16 v[98:101], v[174:177], v[198:201], v[98:101]
	v_mfma_f32_16x16x32_bf16 v[90:93], v[182:185], v[198:201], v[90:93]
	v_mfma_f32_16x16x32_bf16 v[86:89], v[174:177], v[206:209], v[86:89]
	v_mfma_f32_16x16x32_bf16 v[78:81], v[182:185], v[206:209], v[78:81]
	v_mfma_f32_16x16x32_bf16 v[70:73], v[174:177], v[214:217], v[70:73]
	v_mfma_f32_16x16x32_bf16 v[66:69], v[182:185], v[214:217], v[66:69]
	s_setprio 0
	s_barrier
	s_add_i32 s28, s50, s3
	v_lshl_add_u64 v[146:147], s[40:41], 0, v[132:133]
	s_mov_b32 m0, s28
	ds_read_b128 v[186:189], v152 offset:16384
	ds_read_b128 v[190:193], v152 offset:17408
	ds_read_b128 v[194:197], v152 offset:18432
	ds_read_b128 v[198:201], v152 offset:19456
	ds_read_b128 v[202:205], v152 offset:20480
	ds_read_b128 v[206:209], v152 offset:21504
	ds_read_b128 v[210:213], v152 offset:22528
	ds_read_b128 v[214:217], v152 offset:23552
	global_load_lds_dwordx4 v[146:147], off
	s_add_i32 m0, s28, 0x2000
	s_add_u32 s28, s40, 0x2b0000
	v_lshl_add_u64 v[218:219], s[40:41], 0, v[136:137]
	s_addc_u32 s29, s41, 0
	s_add_i32 s75, s51, s3
	global_load_lds_dwordx4 v[218:219], off
	v_lshl_add_u64 v[220:221], s[28:29], 0, v[132:133]
	s_mov_b32 m0, s75
	v_lshl_add_u64 v[222:223], s[62:63], 0, v[134:135]
	global_load_lds_dwordx4 v[220:221], off
	v_lshl_add_u64 v[220:221], s[28:29], 0, v[136:137]
	s_add_i32 m0, s75, 0x2000
	s_nop 0
	global_load_lds_dwordx4 v[220:221], off
	v_lshl_add_u64 v[220:221], s[62:63], 0, v[130:131]
	s_mov_b32 m0, s15
	s_nop 0
	global_load_lds_dwordx4 v[220:221], off
	s_mov_b32 m0, s36
	s_nop 0
	global_load_lds_dwordx4 v[222:223], off
	s_waitcnt vmcnt(8)
	s_waitcnt lgkmcnt(0)
	s_barrier
	s_setprio 1
	s_waitcnt lgkmcnt(0)
	v_mfma_f32_16x16x32_bf16 v[62:65], v[154:157], v[186:189], v[62:65]
	v_mfma_f32_16x16x32_bf16 v[58:61], v[162:165], v[186:189], v[58:61]
	v_mfma_f32_16x16x32_bf16 v[54:57], v[154:157], v[194:197], v[54:57]
	v_mfma_f32_16x16x32_bf16 v[46:49], v[162:165], v[194:197], v[46:49]
	v_mfma_f32_16x16x32_bf16 v[38:41], v[154:157], v[202:205], v[38:41]
	v_mfma_f32_16x16x32_bf16 v[30:33], v[162:165], v[202:205], v[30:33]
	v_mfma_f32_16x16x32_bf16 v[22:25], v[154:157], v[210:213], v[22:25]
	v_mfma_f32_16x16x32_bf16 v[14:17], v[162:165], v[210:213], v[14:17]
	v_mfma_f32_16x16x32_bf16 v[62:65], v[158:161], v[190:193], v[62:65]
	v_mfma_f32_16x16x32_bf16 v[58:61], v[166:169], v[190:193], v[58:61]
	v_mfma_f32_16x16x32_bf16 v[54:57], v[158:161], v[198:201], v[54:57]
	v_mfma_f32_16x16x32_bf16 v[46:49], v[166:169], v[198:201], v[46:49]
	v_mfma_f32_16x16x32_bf16 v[38:41], v[158:161], v[206:209], v[38:41]
	v_mfma_f32_16x16x32_bf16 v[30:33], v[166:169], v[206:209], v[30:33]
	v_mfma_f32_16x16x32_bf16 v[22:25], v[158:161], v[214:217], v[22:25]
	v_mfma_f32_16x16x32_bf16 v[14:17], v[166:169], v[214:217], v[14:17]
	s_setprio 0
	s_setprio 1
	v_mfma_f32_16x16x32_bf16 v[50:53], v[170:173], v[186:189], v[50:53]
	v_mfma_f32_16x16x32_bf16 v[42:45], v[178:181], v[186:189], v[42:45]
	v_mfma_f32_16x16x32_bf16 v[34:37], v[170:173], v[194:197], v[34:37]
	v_mfma_f32_16x16x32_bf16 v[26:29], v[178:181], v[194:197], v[26:29]
	v_mfma_f32_16x16x32_bf16 v[18:21], v[170:173], v[202:205], v[18:21]
	v_mfma_f32_16x16x32_bf16 v[10:13], v[178:181], v[202:205], v[10:13]
	v_mfma_f32_16x16x32_bf16 v[6:9], v[170:173], v[210:213], v[6:9]
	v_mfma_f32_16x16x32_bf16 v[2:5], v[178:181], v[210:213], v[2:5]
	v_mfma_f32_16x16x32_bf16 v[50:53], v[174:177], v[190:193], v[50:53]
	v_mfma_f32_16x16x32_bf16 v[42:45], v[182:185], v[190:193], v[42:45]
	v_mfma_f32_16x16x32_bf16 v[34:37], v[174:177], v[198:201], v[34:37]
	v_mfma_f32_16x16x32_bf16 v[26:29], v[182:185], v[198:201], v[26:29]
	v_mfma_f32_16x16x32_bf16 v[18:21], v[174:177], v[206:209], v[18:21]
	v_mfma_f32_16x16x32_bf16 v[10:13], v[182:185], v[206:209], v[10:13]
	v_mfma_f32_16x16x32_bf16 v[6:9], v[174:177], v[214:217], v[6:9]
	v_mfma_f32_16x16x32_bf16 v[2:5], v[182:185], v[214:217], v[2:5]
	s_setprio 0
	s_barrier
	s_add_i32 s75, 0, 0x18000
	v_add_u32_e32 v153, s75, v148
	s_add_i32 s76, 0, 0x1c000
	ds_read_b128 v[154:157], v153
	ds_read_b128 v[158:161], v153 offset:1024
	ds_read_b128 v[162:165], v153 offset:2048
	ds_read_b128 v[166:169], v153 offset:3072
	v_add_u32_e32 v153, s76, v148
	ds_read_b128 v[170:173], v153
	ds_read_b128 v[174:177], v153 offset:1024
	ds_read_b128 v[178:181], v153 offset:2048
	ds_read_b128 v[182:185], v153 offset:3072
	s_add_u32 s28, s62, 0x2b0000
	s_addc_u32 s29, s63, 0
	s_mov_b32 m0, s37
	v_lshl_add_u64 v[224:225], s[28:29], 0, v[130:131]
	ds_read_b128 v[186:189], v152 offset:32768
	ds_read_b128 v[190:193], v152 offset:33792
	ds_read_b128 v[194:197], v152 offset:34816
	ds_read_b128 v[198:201], v152 offset:35840
	ds_read_b128 v[202:205], v152 offset:36864
	ds_read_b128 v[206:209], v152 offset:37888
	ds_read_b128 v[210:213], v152 offset:38912
	ds_read_b128 v[214:217], v152 offset:39936
	global_load_lds_dwordx4 v[224:225], off
	v_lshl_add_u64 v[224:225], s[28:29], 0, v[134:135]
	s_mov_b32 m0, s42
	s_nop 0
	global_load_lds_dwordx4 v[224:225], off
	s_waitcnt vmcnt(8)
	s_waitcnt lgkmcnt(0)
	s_barrier
	s_setprio 1
	s_waitcnt lgkmcnt(0)
	v_mfma_f32_16x16x32_bf16 v[126:129], v[154:157], v[186:189], v[126:129]
	v_mfma_f32_16x16x32_bf16 v[122:125], v[162:165], v[186:189], v[122:125]
	v_mfma_f32_16x16x32_bf16 v[118:121], v[154:157], v[194:197], v[118:121]
	v_mfma_f32_16x16x32_bf16 v[110:113], v[162:165], v[194:197], v[110:113]
	v_mfma_f32_16x16x32_bf16 v[102:105], v[154:157], v[202:205], v[102:105]
	v_mfma_f32_16x16x32_bf16 v[94:97], v[162:165], v[202:205], v[94:97]
	v_mfma_f32_16x16x32_bf16 v[82:85], v[154:157], v[210:213], v[82:85]
	v_mfma_f32_16x16x32_bf16 v[74:77], v[162:165], v[210:213], v[74:77]
	v_mfma_f32_16x16x32_bf16 v[126:129], v[158:161], v[190:193], v[126:129]
	v_mfma_f32_16x16x32_bf16 v[122:125], v[166:169], v[190:193], v[122:125]
	v_mfma_f32_16x16x32_bf16 v[118:121], v[158:161], v[198:201], v[118:121]
	v_mfma_f32_16x16x32_bf16 v[110:113], v[166:169], v[198:201], v[110:113]
	v_mfma_f32_16x16x32_bf16 v[102:105], v[158:161], v[206:209], v[102:105]
	v_mfma_f32_16x16x32_bf16 v[94:97], v[166:169], v[206:209], v[94:97]
	v_mfma_f32_16x16x32_bf16 v[82:85], v[158:161], v[214:217], v[82:85]
	v_mfma_f32_16x16x32_bf16 v[74:77], v[166:169], v[214:217], v[74:77]
	s_setprio 0
	s_setprio 1
	v_mfma_f32_16x16x32_bf16 v[114:117], v[170:173], v[186:189], v[114:117]
	v_mfma_f32_16x16x32_bf16 v[106:109], v[178:181], v[186:189], v[106:109]
	v_mfma_f32_16x16x32_bf16 v[98:101], v[170:173], v[194:197], v[98:101]
	v_mfma_f32_16x16x32_bf16 v[90:93], v[178:181], v[194:197], v[90:93]
	v_mfma_f32_16x16x32_bf16 v[86:89], v[170:173], v[202:205], v[86:89]
	v_mfma_f32_16x16x32_bf16 v[78:81], v[178:181], v[202:205], v[78:81]
	v_mfma_f32_16x16x32_bf16 v[70:73], v[170:173], v[210:213], v[70:73]
	v_mfma_f32_16x16x32_bf16 v[66:69], v[178:181], v[210:213], v[66:69]
	v_mfma_f32_16x16x32_bf16 v[114:117], v[174:177], v[190:193], v[114:117]
	v_mfma_f32_16x16x32_bf16 v[106:109], v[182:185], v[190:193], v[106:109]
	v_mfma_f32_16x16x32_bf16 v[98:101], v[174:177], v[198:201], v[98:101]
	v_mfma_f32_16x16x32_bf16 v[90:93], v[182:185], v[198:201], v[90:93]
	v_mfma_f32_16x16x32_bf16 v[86:89], v[174:177], v[206:209], v[86:89]
	v_mfma_f32_16x16x32_bf16 v[78:81], v[182:185], v[206:209], v[78:81]
	v_mfma_f32_16x16x32_bf16 v[70:73], v[174:177], v[214:217], v[70:73]
	v_mfma_f32_16x16x32_bf16 v[66:69], v[182:185], v[214:217], v[66:69]
	s_setprio 0
	s_barrier
	s_add_i32 s28, s75, s3
	v_lshl_add_u64 v[146:147], v[146:147], 0, s[22:23]
	s_mov_b32 m0, s28
	ds_read_b128 v[186:189], v152 offset:49152
	ds_read_b128 v[190:193], v152 offset:50176
	ds_read_b128 v[194:197], v152 offset:51200
	ds_read_b128 v[198:201], v152 offset:52224
	ds_read_b128 v[202:205], v152 offset:53248
	ds_read_b128 v[206:209], v152 offset:54272
	ds_read_b128 v[210:213], v152 offset:55296
	ds_read_b128 v[214:217], v152 offset:56320
	global_load_lds_dwordx4 v[146:147], off
	s_add_i32 m0, s28, 0x2000
	s_add_u32 s28, s40, 0x2b0080
	v_lshl_add_u64 v[146:147], v[218:219], 0, s[22:23]
	s_addc_u32 s29, s41, 0
	s_add_i32 s40, s76, s3
	global_load_lds_dwordx4 v[146:147], off
	v_lshl_add_u64 v[146:147], s[28:29], 0, v[132:133]
	s_mov_b32 m0, s40
	s_nop 0
	global_load_lds_dwordx4 v[146:147], off
	v_lshl_add_u64 v[146:147], s[28:29], 0, v[136:137]
	s_add_i32 m0, s40, 0x2000
	s_nop 0
	global_load_lds_dwordx4 v[146:147], off
	v_lshl_add_u64 v[146:147], v[220:221], 0, s[22:23]
	s_mov_b32 m0, s44
	s_nop 0
	global_load_lds_dwordx4 v[146:147], off
	v_lshl_add_u64 v[146:147], v[222:223], 0, s[22:23]
	s_mov_b32 m0, s45
	s_nop 0
	global_load_lds_dwordx4 v[146:147], off
	s_waitcnt vmcnt(8)
	s_waitcnt lgkmcnt(0)
	s_barrier
	s_setprio 1
	s_waitcnt lgkmcnt(0)
	v_mfma_f32_16x16x32_bf16 v[62:65], v[154:157], v[186:189], v[62:65]
	v_mfma_f32_16x16x32_bf16 v[58:61], v[162:165], v[186:189], v[58:61]
	v_mfma_f32_16x16x32_bf16 v[54:57], v[154:157], v[194:197], v[54:57]
	v_mfma_f32_16x16x32_bf16 v[46:49], v[162:165], v[194:197], v[46:49]
	v_mfma_f32_16x16x32_bf16 v[38:41], v[154:157], v[202:205], v[38:41]
	v_mfma_f32_16x16x32_bf16 v[30:33], v[162:165], v[202:205], v[30:33]
	v_mfma_f32_16x16x32_bf16 v[22:25], v[154:157], v[210:213], v[22:25]
	v_mfma_f32_16x16x32_bf16 v[14:17], v[162:165], v[210:213], v[14:17]
	v_mfma_f32_16x16x32_bf16 v[62:65], v[158:161], v[190:193], v[62:65]
	v_mfma_f32_16x16x32_bf16 v[58:61], v[166:169], v[190:193], v[58:61]
	v_mfma_f32_16x16x32_bf16 v[54:57], v[158:161], v[198:201], v[54:57]
	v_mfma_f32_16x16x32_bf16 v[46:49], v[166:169], v[198:201], v[46:49]
	v_mfma_f32_16x16x32_bf16 v[38:41], v[158:161], v[206:209], v[38:41]
	v_mfma_f32_16x16x32_bf16 v[30:33], v[166:169], v[206:209], v[30:33]
	v_mfma_f32_16x16x32_bf16 v[22:25], v[158:161], v[214:217], v[22:25]
	v_mfma_f32_16x16x32_bf16 v[14:17], v[166:169], v[214:217], v[14:17]
	s_setprio 0
	s_setprio 1
	v_mfma_f32_16x16x32_bf16 v[50:53], v[170:173], v[186:189], v[50:53]
	v_mfma_f32_16x16x32_bf16 v[42:45], v[178:181], v[186:189], v[42:45]
	v_mfma_f32_16x16x32_bf16 v[34:37], v[170:173], v[194:197], v[34:37]
	v_mfma_f32_16x16x32_bf16 v[26:29], v[178:181], v[194:197], v[26:29]
	v_mfma_f32_16x16x32_bf16 v[18:21], v[170:173], v[202:205], v[18:21]
	v_mfma_f32_16x16x32_bf16 v[10:13], v[178:181], v[202:205], v[10:13]
	v_mfma_f32_16x16x32_bf16 v[6:9], v[170:173], v[210:213], v[6:9]
	v_mfma_f32_16x16x32_bf16 v[2:5], v[178:181], v[210:213], v[2:5]
	v_mfma_f32_16x16x32_bf16 v[50:53], v[174:177], v[190:193], v[50:53]
	v_mfma_f32_16x16x32_bf16 v[42:45], v[182:185], v[190:193], v[42:45]
	v_mfma_f32_16x16x32_bf16 v[34:37], v[174:177], v[198:201], v[34:37]
	v_mfma_f32_16x16x32_bf16 v[26:29], v[182:185], v[198:201], v[26:29]
	v_mfma_f32_16x16x32_bf16 v[18:21], v[174:177], v[206:209], v[18:21]
	v_mfma_f32_16x16x32_bf16 v[10:13], v[182:185], v[206:209], v[10:13]
	v_mfma_f32_16x16x32_bf16 v[6:9], v[174:177], v[214:217], v[6:9]
	v_mfma_f32_16x16x32_bf16 v[2:5], v[182:185], v[214:217], v[2:5]
	s_setprio 0
	s_barrier
	ds_read_b128 v[154:157], v150
	ds_read_b128 v[158:161], v150 offset:1024
	ds_read_b128 v[162:165], v150 offset:2048
	ds_read_b128 v[166:169], v150 offset:3072
	ds_read_b128 v[170:173], v151
	ds_read_b128 v[174:177], v151 offset:1024
	ds_read_b128 v[178:181], v151 offset:2048
	ds_read_b128 v[182:185], v151 offset:3072
	s_add_i32 s74, s74, 2
	s_add_u32 s72, s72, 0x100
	s_addc_u32 s73, s73, 0
	s_cmpk_gt_u32 s74, 0xa9
	s_mov_b64 s[28:29], s[30:31]
	s_cbranch_scc0 .Lkrot_260
	s_waitcnt lgkmcnt(0)
	s_and_b64 vcc, exec, s[24:25]
	s_cbranch_vccz .LBB0_263
	s_barrier

.Lkrot_387:
	s_add_u32 s40, s30, 0xfff00080
	s_addc_u32 s41, s31, -1
	s_cmp_eq_u32 s71, 60
	s_cselect_b32 s69, s23, s41
	s_cselect_b32 s68, s63, s40
	s_cselect_b32 s41, s13, s70
	s_cselect_b32 s40, s66, s67
	v_lshl_add_u64 v[144:145], s[30:31], 0, v[134:135]
	s_add_i32 m0, s29, 0xc000
	ds_read_b128 v[184:187], v150
	ds_read_b128 v[188:191], v150 offset:1024
	ds_read_b128 v[192:195], v150 offset:2048
	ds_read_b128 v[196:199], v150 offset:3072
	ds_read_b128 v[200:203], v150 offset:4096
	ds_read_b128 v[204:207], v150 offset:5120
	ds_read_b128 v[208:211], v150 offset:6144
	ds_read_b128 v[212:215], v150 offset:7168
	global_load_lds_dwordx4 v[144:145], off
	v_lshl_add_u64 v[144:145], s[30:31], 0, v[136:137]
	s_add_i32 m0, s29, 0xe000
	s_nop 0
	global_load_lds_dwordx4 v[144:145], off
	s_waitcnt vmcnt(8)
	s_waitcnt lgkmcnt(0)
	s_barrier
	s_setprio 1
	s_waitcnt lgkmcnt(0)
	v_mfma_f32_16x16x32_bf16 v[126:129], v[152:155], v[184:187], v[126:129]
	v_mfma_f32_16x16x32_bf16 v[122:125], v[160:163], v[184:187], v[122:125]
	v_mfma_f32_16x16x32_bf16 v[114:117], v[152:155], v[192:195], v[114:117]
	v_mfma_f32_16x16x32_bf16 v[106:109], v[160:163], v[192:195], v[106:109]
	v_mfma_f32_16x16x32_bf16 v[98:101], v[152:155], v[200:203], v[98:101]
	v_mfma_f32_16x16x32_bf16 v[90:93], v[160:163], v[200:203], v[90:93]
	v_mfma_f32_16x16x32_bf16 v[82:85], v[152:155], v[208:211], v[82:85]
	v_mfma_f32_16x16x32_bf16 v[74:77], v[160:163], v[208:211], v[74:77]
	v_mfma_f32_16x16x32_bf16 v[126:129], v[156:159], v[188:191], v[126:129]
	v_mfma_f32_16x16x32_bf16 v[122:125], v[164:167], v[188:191], v[122:125]
	v_mfma_f32_16x16x32_bf16 v[114:117], v[156:159], v[196:199], v[114:117]
	v_mfma_f32_16x16x32_bf16 v[106:109], v[164:167], v[196:199], v[106:109]
	v_mfma_f32_16x16x32_bf16 v[98:101], v[156:159], v[204:207], v[98:101]
	v_mfma_f32_16x16x32_bf16 v[90:93], v[164:167], v[204:207], v[90:93]
	v_mfma_f32_16x16x32_bf16 v[82:85], v[156:159], v[212:215], v[82:85]
	v_mfma_f32_16x16x32_bf16 v[74:77], v[164:167], v[212:215], v[74:77]
	s_setprio 0
	s_setprio 1
	v_mfma_f32_16x16x32_bf16 v[118:121], v[168:171], v[184:187], v[118:121]
	v_mfma_f32_16x16x32_bf16 v[110:113], v[176:179], v[184:187], v[110:113]
	v_mfma_f32_16x16x32_bf16 v[102:105], v[168:171], v[192:195], v[102:105]
	v_mfma_f32_16x16x32_bf16 v[94:97], v[176:179], v[192:195], v[94:97]
	v_mfma_f32_16x16x32_bf16 v[86:89], v[168:171], v[200:203], v[86:89]
	v_mfma_f32_16x16x32_bf16 v[78:81], v[176:179], v[200:203], v[78:81]
	v_mfma_f32_16x16x32_bf16 v[70:73], v[168:171], v[208:211], v[70:73]
	v_mfma_f32_16x16x32_bf16 v[66:69], v[176:179], v[208:211], v[66:69]
	v_mfma_f32_16x16x32_bf16 v[118:121], v[172:175], v[188:191], v[118:121]
	v_mfma_f32_16x16x32_bf16 v[110:113], v[180:183], v[188:191], v[110:113]
	v_mfma_f32_16x16x32_bf16 v[102:105], v[172:175], v[196:199], v[102:105]
	v_mfma_f32_16x16x32_bf16 v[94:97], v[180:183], v[196:199], v[94:97]
	v_mfma_f32_16x16x32_bf16 v[86:89], v[172:175], v[204:207], v[86:89]
	v_mfma_f32_16x16x32_bf16 v[78:81], v[180:183], v[204:207], v[78:81]
	v_mfma_f32_16x16x32_bf16 v[70:73], v[172:175], v[212:215], v[70:73]
	v_mfma_f32_16x16x32_bf16 v[66:69], v[180:183], v[212:215], v[66:69]
	s_setprio 0
	s_barrier
	s_add_i32 s72, s50, s36
	v_lshl_add_u64 v[144:145], s[40:41], 0, v[132:133]
	s_mov_b32 m0, s72
	ds_read_b128 v[184:187], v150 offset:16384
	ds_read_b128 v[188:191], v150 offset:17408
	ds_read_b128 v[192:195], v150 offset:18432
	ds_read_b128 v[196:199], v150 offset:19456
	ds_read_b128 v[200:203], v150 offset:20480
	ds_read_b128 v[204:207], v150 offset:21504
	ds_read_b128 v[208:211], v150 offset:22528
	ds_read_b128 v[212:215], v150 offset:23552
	global_load_lds_dwordx4 v[144:145], off
	s_add_i32 m0, s72, 0x2000
	s_add_u32 s72, s40, 0x100000
	v_lshl_add_u64 v[216:217], s[40:41], 0, v[130:131]
	s_addc_u32 s73, s41, 0
	s_add_i32 s74, s51, s36
	global_load_lds_dwordx4 v[216:217], off
	v_lshl_add_u64 v[218:219], s[72:73], 0, v[132:133]
	s_mov_b32 m0, s74
	v_lshl_add_u64 v[220:221], s[68:69], 0, v[130:131]
	global_load_lds_dwordx4 v[218:219], off
	v_lshl_add_u64 v[218:219], s[72:73], 0, v[130:131]
	s_add_i32 m0, s74, 0x2000
	s_nop 0
	global_load_lds_dwordx4 v[218:219], off
	v_lshl_add_u64 v[218:219], s[68:69], 0, v[132:133]
	s_mov_b32 m0, s29
	s_nop 0
	global_load_lds_dwordx4 v[218:219], off
	s_mov_b32 m0, s43
	s_nop 0
	global_load_lds_dwordx4 v[220:221], off
	s_waitcnt vmcnt(8)
	s_waitcnt lgkmcnt(0)
	s_barrier
	s_setprio 1
	s_waitcnt lgkmcnt(0)
	v_mfma_f32_16x16x32_bf16 v[62:65], v[152:155], v[184:187], v[62:65]
	v_mfma_f32_16x16x32_bf16 v[58:61], v[160:163], v[184:187], v[58:61]
	v_mfma_f32_16x16x32_bf16 v[50:53], v[152:155], v[192:195], v[50:53]
	v_mfma_f32_16x16x32_bf16 v[42:45], v[160:163], v[192:195], v[42:45]
	v_mfma_f32_16x16x32_bf16 v[34:37], v[152:155], v[200:203], v[34:37]
	v_mfma_f32_16x16x32_bf16 v[26:29], v[160:163], v[200:203], v[26:29]
	v_mfma_f32_16x16x32_bf16 v[18:21], v[152:155], v[208:211], v[18:21]
	v_mfma_f32_16x16x32_bf16 v[10:13], v[160:163], v[208:211], v[10:13]
	v_mfma_f32_16x16x32_bf16 v[62:65], v[156:159], v[188:191], v[62:65]
	v_mfma_f32_16x16x32_bf16 v[58:61], v[164:167], v[188:191], v[58:61]
	v_mfma_f32_16x16x32_bf16 v[50:53], v[156:159], v[196:199], v[50:53]
	v_mfma_f32_16x16x32_bf16 v[42:45], v[164:167], v[196:199], v[42:45]
	v_mfma_f32_16x16x32_bf16 v[34:37], v[156:159], v[204:207], v[34:37]
	v_mfma_f32_16x16x32_bf16 v[26:29], v[164:167], v[204:207], v[26:29]
	v_mfma_f32_16x16x32_bf16 v[18:21], v[156:159], v[212:215], v[18:21]
	v_mfma_f32_16x16x32_bf16 v[10:13], v[164:167], v[212:215], v[10:13]
	s_setprio 0
	s_setprio 1
	v_mfma_f32_16x16x32_bf16 v[54:57], v[168:171], v[184:187], v[54:57]
	v_mfma_f32_16x16x32_bf16 v[46:49], v[176:179], v[184:187], v[46:49]
	v_mfma_f32_16x16x32_bf16 v[38:41], v[168:171], v[192:195], v[38:41]
	v_mfma_f32_16x16x32_bf16 v[30:33], v[176:179], v[192:195], v[30:33]
	v_mfma_f32_16x16x32_bf16 v[22:25], v[168:171], v[200:203], v[22:25]
	v_mfma_f32_16x16x32_bf16 v[14:17], v[176:179], v[200:203], v[14:17]
	v_mfma_f32_16x16x32_bf16 v[6:9], v[168:171], v[208:211], v[6:9]
	v_mfma_f32_16x16x32_bf16 v[2:5], v[176:179], v[208:211], v[2:5]
	v_mfma_f32_16x16x32_bf16 v[54:57], v[172:175], v[188:191], v[54:57]
	v_mfma_f32_16x16x32_bf16 v[46:49], v[180:183], v[188:191], v[46:49]
	v_mfma_f32_16x16x32_bf16 v[38:41], v[172:175], v[196:199], v[38:41]
	v_mfma_f32_16x16x32_bf16 v[30:33], v[180:183], v[196:199], v[30:33]
	v_mfma_f32_16x16x32_bf16 v[22:25], v[172:175], v[204:207], v[22:25]
	v_mfma_f32_16x16x32_bf16 v[14:17], v[180:183], v[204:207], v[14:17]
	v_mfma_f32_16x16x32_bf16 v[6:9], v[172:175], v[212:215], v[6:9]
	v_mfma_f32_16x16x32_bf16 v[2:5], v[180:183], v[212:215], v[2:5]
	s_setprio 0
	s_barrier
	s_add_i32 s72, 0, 0x18000
	v_add_u32_e32 v142, s72, v146
	s_add_i32 s73, 0, 0x1c000
	ds_read_b128 v[152:155], v142
	ds_read_b128 v[156:159], v142 offset:1024
	ds_read_b128 v[160:163], v142 offset:2048
	ds_read_b128 v[164:167], v142 offset:3072
	v_add_u32_e32 v142, s73, v146
	ds_read_b128 v[168:171], v142
	ds_read_b128 v[172:175], v142 offset:1024
	ds_read_b128 v[176:179], v142 offset:2048
	ds_read_b128 v[180:183], v142 offset:3072
	s_add_u32 s68, s68, 0x100000
	s_addc_u32 s69, s69, 0
	s_mov_b32 m0, s44
	v_lshl_add_u64 v[222:223], s[68:69], 0, v[132:133]
	ds_read_b128 v[184:187], v150 offset:32768
	ds_read_b128 v[188:191], v150 offset:33792
	ds_read_b128 v[192:195], v150 offset:34816
	ds_read_b128 v[196:199], v150 offset:35840
	ds_read_b128 v[200:203], v150 offset:36864
	ds_read_b128 v[204:207], v150 offset:37888
	ds_read_b128 v[208:211], v150 offset:38912
	ds_read_b128 v[212:215], v150 offset:39936
	global_load_lds_dwordx4 v[222:223], off
	v_lshl_add_u64 v[222:223], s[68:69], 0, v[130:131]
	s_mov_b32 m0, s45
	s_nop 0
	global_load_lds_dwordx4 v[222:223], off
	s_waitcnt vmcnt(8)
	s_waitcnt lgkmcnt(0)
	s_barrier
	s_setprio 1
	s_waitcnt lgkmcnt(0)
	v_mfma_f32_16x16x32_bf16 v[126:129], v[152:155], v[184:187], v[126:129]
	v_mfma_f32_16x16x32_bf16 v[122:125], v[160:163], v[184:187], v[122:125]
	v_mfma_f32_16x16x32_bf16 v[114:117], v[152:155], v[192:195], v[114:117]
	v_mfma_f32_16x16x32_bf16 v[106:109], v[160:163], v[192:195], v[106:109]
	v_mfma_f32_16x16x32_bf16 v[98:101], v[152:155], v[200:203], v[98:101]
	v_mfma_f32_16x16x32_bf16 v[90:93], v[160:163], v[200:203], v[90:93]
	v_mfma_f32_16x16x32_bf16 v[82:85], v[152:155], v[208:211], v[82:85]
	v_mfma_f32_16x16x32_bf16 v[74:77], v[160:163], v[208:211], v[74:77]
	v_mfma_f32_16x16x32_bf16 v[126:129], v[156:159], v[188:191], v[126:129]
	v_mfma_f32_16x16x32_bf16 v[122:125], v[164:167], v[188:191], v[122:125]
	v_mfma_f32_16x16x32_bf16 v[114:117], v[156:159], v[196:199], v[114:117]
	v_mfma_f32_16x16x32_bf16 v[106:109], v[164:167], v[196:199], v[106:109]
	v_mfma_f32_16x16x32_bf16 v[98:101], v[156:159], v[204:207], v[98:101]
	v_mfma_f32_16x16x32_bf16 v[90:93], v[164:167], v[204:207], v[90:93]
	v_mfma_f32_16x16x32_bf16 v[82:85], v[156:159], v[212:215], v[82:85]
	v_mfma_f32_16x16x32_bf16 v[74:77], v[164:167], v[212:215], v[74:77]
	s_setprio 0
	s_setprio 1
	v_mfma_f32_16x16x32_bf16 v[118:121], v[168:171], v[184:187], v[118:121]
	v_mfma_f32_16x16x32_bf16 v[110:113], v[176:179], v[184:187], v[110:113]
	v_mfma_f32_16x16x32_bf16 v[102:105], v[168:171], v[192:195], v[102:105]
	v_mfma_f32_16x16x32_bf16 v[94:97], v[176:179], v[192:195], v[94:97]
	v_mfma_f32_16x16x32_bf16 v[86:89], v[168:171], v[200:203], v[86:89]
	v_mfma_f32_16x16x32_bf16 v[78:81], v[176:179], v[200:203], v[78:81]
	v_mfma_f32_16x16x32_bf16 v[70:73], v[168:171], v[208:211], v[70:73]
	v_mfma_f32_16x16x32_bf16 v[66:69], v[176:179], v[208:211], v[66:69]
	v_mfma_f32_16x16x32_bf16 v[118:121], v[172:175], v[188:191], v[118:121]
	v_mfma_f32_16x16x32_bf16 v[110:113], v[180:183], v[188:191], v[110:113]
	v_mfma_f32_16x16x32_bf16 v[102:105], v[172:175], v[196:199], v[102:105]
	v_mfma_f32_16x16x32_bf16 v[94:97], v[180:183], v[196:199], v[94:97]
	v_mfma_f32_16x16x32_bf16 v[86:89], v[172:175], v[204:207], v[86:89]
	v_mfma_f32_16x16x32_bf16 v[78:81], v[180:183], v[204:207], v[78:81]
	v_mfma_f32_16x16x32_bf16 v[70:73], v[172:175], v[212:215], v[70:73]
	v_mfma_f32_16x16x32_bf16 v[66:69], v[180:183], v[212:215], v[66:69]
	s_setprio 0
	s_barrier
	s_add_i32 s68, s72, s36
	v_lshl_add_u64 v[144:145], v[144:145], 0, s[8:9]
	s_mov_b32 m0, s68
	ds_read_b128 v[184:187], v150 offset:49152
	ds_read_b128 v[188:191], v150 offset:50176
	ds_read_b128 v[192:195], v150 offset:51200
	ds_read_b128 v[196:199], v150 offset:52224
	ds_read_b128 v[200:203], v150 offset:53248
	ds_read_b128 v[204:207], v150 offset:54272
	ds_read_b128 v[208:211], v150 offset:55296
	ds_read_b128 v[212:215], v150 offset:56320
	global_load_lds_dwordx4 v[144:145], off
	s_add_i32 m0, s68, 0x2000
	s_add_u32 s40, s40, 0x100080
	v_lshl_add_u64 v[144:145], v[216:217], 0, s[8:9]
	s_addc_u32 s41, s41, 0
	s_add_i32 s68, s73, s36
	global_load_lds_dwordx4 v[144:145], off
	v_lshl_add_u64 v[144:145], s[40:41], 0, v[132:133]
	s_mov_b32 m0, s68
	s_nop 0
	global_load_lds_dwordx4 v[144:145], off
	v_lshl_add_u64 v[144:145], s[40:41], 0, v[130:131]
	s_add_i32 m0, s68, 0x2000
	s_nop 0
	global_load_lds_dwordx4 v[144:145], off
	v_lshl_add_u64 v[144:145], v[218:219], 0, s[8:9]
	s_mov_b32 m0, s47
	s_nop 0
	global_load_lds_dwordx4 v[144:145], off
	v_lshl_add_u64 v[144:145], v[220:221], 0, s[8:9]
	s_mov_b32 m0, s48
	s_nop 0
	global_load_lds_dwordx4 v[144:145], off
	s_waitcnt vmcnt(8)
	s_waitcnt lgkmcnt(0)
	s_barrier
	s_setprio 1
	s_waitcnt lgkmcnt(0)
	v_mfma_f32_16x16x32_bf16 v[62:65], v[152:155], v[184:187], v[62:65]
	v_mfma_f32_16x16x32_bf16 v[58:61], v[160:163], v[184:187], v[58:61]
	v_mfma_f32_16x16x32_bf16 v[50:53], v[152:155], v[192:195], v[50:53]
	v_mfma_f32_16x16x32_bf16 v[42:45], v[160:163], v[192:195], v[42:45]
	v_mfma_f32_16x16x32_bf16 v[34:37], v[152:155], v[200:203], v[34:37]
	v_mfma_f32_16x16x32_bf16 v[26:29], v[160:163], v[200:203], v[26:29]
	v_mfma_f32_16x16x32_bf16 v[18:21], v[152:155], v[208:211], v[18:21]
	v_mfma_f32_16x16x32_bf16 v[10:13], v[160:163], v[208:211], v[10:13]
	v_mfma_f32_16x16x32_bf16 v[62:65], v[156:159], v[188:191], v[62:65]
	v_mfma_f32_16x16x32_bf16 v[58:61], v[164:167], v[188:191], v[58:61]
	v_mfma_f32_16x16x32_bf16 v[50:53], v[156:159], v[196:199], v[50:53]
	v_mfma_f32_16x16x32_bf16 v[42:45], v[164:167], v[196:199], v[42:45]
	v_mfma_f32_16x16x32_bf16 v[34:37], v[156:159], v[204:207], v[34:37]
	v_mfma_f32_16x16x32_bf16 v[26:29], v[164:167], v[204:207], v[26:29]
	v_mfma_f32_16x16x32_bf16 v[18:21], v[156:159], v[212:215], v[18:21]
	v_mfma_f32_16x16x32_bf16 v[10:13], v[164:167], v[212:215], v[10:13]
	s_setprio 0
	s_setprio 1
	v_mfma_f32_16x16x32_bf16 v[54:57], v[168:171], v[184:187], v[54:57]
	v_mfma_f32_16x16x32_bf16 v[46:49], v[176:179], v[184:187], v[46:49]
	v_mfma_f32_16x16x32_bf16 v[38:41], v[168:171], v[192:195], v[38:41]
	v_mfma_f32_16x16x32_bf16 v[30:33], v[176:179], v[192:195], v[30:33]
	v_mfma_f32_16x16x32_bf16 v[22:25], v[168:171], v[200:203], v[22:25]
	v_mfma_f32_16x16x32_bf16 v[14:17], v[176:179], v[200:203], v[14:17]
	v_mfma_f32_16x16x32_bf16 v[6:9], v[168:171], v[208:211], v[6:9]
	v_mfma_f32_16x16x32_bf16 v[2:5], v[176:179], v[208:211], v[2:5]
	v_mfma_f32_16x16x32_bf16 v[54:57], v[172:175], v[188:191], v[54:57]
	v_mfma_f32_16x16x32_bf16 v[46:49], v[180:183], v[188:191], v[46:49]
	v_mfma_f32_16x16x32_bf16 v[38:41], v[172:175], v[196:199], v[38:41]
	v_mfma_f32_16x16x32_bf16 v[30:33], v[180:183], v[196:199], v[30:33]
	v_mfma_f32_16x16x32_bf16 v[22:25], v[172:175], v[204:207], v[22:25]
	v_mfma_f32_16x16x32_bf16 v[14:17], v[180:183], v[204:207], v[14:17]
	v_mfma_f32_16x16x32_bf16 v[6:9], v[172:175], v[212:215], v[6:9]
	v_mfma_f32_16x16x32_bf16 v[2:5], v[180:183], v[212:215], v[2:5]
	s_setprio 0
	s_barrier
	ds_read_b128 v[152:155], v148
	ds_read_b128 v[156:159], v148 offset:1024
	ds_read_b128 v[160:163], v148 offset:2048
	ds_read_b128 v[164:167], v148 offset:3072
	ds_read_b128 v[168:171], v149
	ds_read_b128 v[172:175], v149 offset:1024
	ds_read_b128 v[176:179], v149 offset:2048
	ds_read_b128 v[180:183], v149 offset:3072
	s_add_i32 s71, s71, 2
	s_add_u32 s30, s30, 0x100
	s_addc_u32 s31, s31, 0
	s_add_u32 s67, s67, 0x100
	s_addc_u32 s70, s70, 0
	s_cmp_gt_u32 s71, 61
	s_cbranch_scc0 .Lkrot_387
	s_waitcnt lgkmcnt(0)
	s_and_b64 vcc, exec, s[10:11]
	s_cbranch_vccz .LBB0_390
	s_barrier

.Lkrot_1211:
	s_add_u32 s40, s36, 0xfff00080
	s_addc_u32 s41, s37, -1
	s_cmp_eq_u32 s64, 60
	s_cselect_b32 s43, s25, s41
	s_cselect_b32 s42, s60, s40
	s_cselect_b32 s41, s23, s63
	s_cselect_b32 s40, s61, s62
	v_lshl_add_u64 v[146:147], s[36:37], 0, v[138:139]
	s_add_i32 m0, s31, 0xc000
	ds_read_b128 v[186:189], v152
	ds_read_b128 v[190:193], v152 offset:1024
	ds_read_b128 v[194:197], v152 offset:2048
	ds_read_b128 v[198:201], v152 offset:3072
	ds_read_b128 v[202:205], v152 offset:4096
	ds_read_b128 v[206:209], v152 offset:5120
	ds_read_b128 v[210:213], v152 offset:6144
	ds_read_b128 v[214:217], v152 offset:7168
	global_load_lds_dwordx4 v[146:147], off
	v_lshl_add_u64 v[146:147], s[36:37], 0, v[140:141]
	s_add_i32 m0, s31, 0xe000
	s_nop 0
	global_load_lds_dwordx4 v[146:147], off
	s_waitcnt vmcnt(8)
	s_waitcnt lgkmcnt(0)
	s_barrier
	s_setprio 1
	s_waitcnt lgkmcnt(0)
	v_mfma_f32_16x16x32_bf16 v[126:129], v[154:157], v[186:189], v[126:129]
	v_mfma_f32_16x16x32_bf16 v[122:125], v[162:165], v[186:189], v[122:125]
	v_mfma_f32_16x16x32_bf16 v[118:121], v[154:157], v[194:197], v[118:121]
	v_mfma_f32_16x16x32_bf16 v[110:113], v[162:165], v[194:197], v[110:113]
	v_mfma_f32_16x16x32_bf16 v[102:105], v[154:157], v[202:205], v[102:105]
	v_mfma_f32_16x16x32_bf16 v[94:97], v[162:165], v[202:205], v[94:97]
	v_mfma_f32_16x16x32_bf16 v[86:89], v[154:157], v[210:213], v[86:89]
	v_mfma_f32_16x16x32_bf16 v[78:81], v[162:165], v[210:213], v[78:81]
	v_mfma_f32_16x16x32_bf16 v[126:129], v[158:161], v[190:193], v[126:129]
	v_mfma_f32_16x16x32_bf16 v[122:125], v[166:169], v[190:193], v[122:125]
	v_mfma_f32_16x16x32_bf16 v[118:121], v[158:161], v[198:201], v[118:121]
	v_mfma_f32_16x16x32_bf16 v[110:113], v[166:169], v[198:201], v[110:113]
	v_mfma_f32_16x16x32_bf16 v[102:105], v[158:161], v[206:209], v[102:105]
	v_mfma_f32_16x16x32_bf16 v[94:97], v[166:169], v[206:209], v[94:97]
	v_mfma_f32_16x16x32_bf16 v[86:89], v[158:161], v[214:217], v[86:89]
	v_mfma_f32_16x16x32_bf16 v[78:81], v[166:169], v[214:217], v[78:81]
	s_setprio 0
	s_setprio 1
	v_mfma_f32_16x16x32_bf16 v[114:117], v[170:173], v[186:189], v[114:117]
	v_mfma_f32_16x16x32_bf16 v[106:109], v[178:181], v[186:189], v[106:109]
	v_mfma_f32_16x16x32_bf16 v[98:101], v[170:173], v[194:197], v[98:101]
	v_mfma_f32_16x16x32_bf16 v[90:93], v[178:181], v[194:197], v[90:93]
	v_mfma_f32_16x16x32_bf16 v[82:85], v[170:173], v[202:205], v[82:85]
	v_mfma_f32_16x16x32_bf16 v[74:77], v[178:181], v[202:205], v[74:77]
	v_mfma_f32_16x16x32_bf16 v[70:73], v[170:173], v[210:213], v[70:73]
	v_mfma_f32_16x16x32_bf16 v[66:69], v[178:181], v[210:213], v[66:69]
	v_mfma_f32_16x16x32_bf16 v[114:117], v[174:177], v[190:193], v[114:117]
	v_mfma_f32_16x16x32_bf16 v[106:109], v[182:185], v[190:193], v[106:109]
	v_mfma_f32_16x16x32_bf16 v[98:101], v[174:177], v[198:201], v[98:101]
	v_mfma_f32_16x16x32_bf16 v[90:93], v[182:185], v[198:201], v[90:93]
	v_mfma_f32_16x16x32_bf16 v[82:85], v[174:177], v[206:209], v[82:85]
	v_mfma_f32_16x16x32_bf16 v[74:77], v[182:185], v[206:209], v[74:77]
	v_mfma_f32_16x16x32_bf16 v[70:73], v[174:177], v[214:217], v[70:73]
	v_mfma_f32_16x16x32_bf16 v[66:69], v[182:185], v[214:217], v[66:69]
	s_setprio 0
	s_barrier
	s_add_i32 s65, s51, s15
	v_lshl_add_u64 v[146:147], s[40:41], 0, v[132:133]
	s_mov_b32 m0, s65
	ds_read_b128 v[186:189], v152 offset:16384
	ds_read_b128 v[190:193], v152 offset:17408
	ds_read_b128 v[194:197], v152 offset:18432
	ds_read_b128 v[198:201], v152 offset:19456
	ds_read_b128 v[202:205], v152 offset:20480
	ds_read_b128 v[206:209], v152 offset:21504
	ds_read_b128 v[210:213], v152 offset:22528
	ds_read_b128 v[214:217], v152 offset:23552
	global_load_lds_dwordx4 v[146:147], off
	s_add_i32 m0, s65, 0x2000
	s_add_u32 s66, s40, 0x100000
	v_lshl_add_u64 v[218:219], s[40:41], 0, v[136:137]
	s_addc_u32 s67, s41, 0
	s_add_i32 s65, s52, s15
	global_load_lds_dwordx4 v[218:219], off
	v_lshl_add_u64 v[220:221], s[66:67], 0, v[132:133]
	s_mov_b32 m0, s65
	v_lshl_add_u64 v[222:223], s[42:43], 0, v[134:135]
	global_load_lds_dwordx4 v[220:221], off
	v_lshl_add_u64 v[220:221], s[66:67], 0, v[136:137]
	s_add_i32 m0, s65, 0x2000
	s_nop 0
	global_load_lds_dwordx4 v[220:221], off
	v_lshl_add_u64 v[220:221], s[42:43], 0, v[130:131]
	s_mov_b32 m0, s31
	s_nop 0
	global_load_lds_dwordx4 v[220:221], off
	s_mov_b32 m0, s44
	s_nop 0
	global_load_lds_dwordx4 v[222:223], off
	s_waitcnt vmcnt(8)
	s_waitcnt lgkmcnt(0)
	s_barrier
	s_setprio 1
	s_waitcnt lgkmcnt(0)
	v_mfma_f32_16x16x32_bf16 v[62:65], v[154:157], v[186:189], v[62:65]
	v_mfma_f32_16x16x32_bf16 v[58:61], v[162:165], v[186:189], v[58:61]
	v_mfma_f32_16x16x32_bf16 v[54:57], v[154:157], v[194:197], v[54:57]
	v_mfma_f32_16x16x32_bf16 v[46:49], v[162:165], v[194:197], v[46:49]
	v_mfma_f32_16x16x32_bf16 v[38:41], v[154:157], v[202:205], v[38:41]
	v_mfma_f32_16x16x32_bf16 v[30:33], v[162:165], v[202:205], v[30:33]
	v_mfma_f32_16x16x32_bf16 v[22:25], v[154:157], v[210:213], v[22:25]
	v_mfma_f32_16x16x32_bf16 v[14:17], v[162:165], v[210:213], v[14:17]
	v_mfma_f32_16x16x32_bf16 v[62:65], v[158:161], v[190:193], v[62:65]
	v_mfma_f32_16x16x32_bf16 v[58:61], v[166:169], v[190:193], v[58:61]
	v_mfma_f32_16x16x32_bf16 v[54:57], v[158:161], v[198:201], v[54:57]
	v_mfma_f32_16x16x32_bf16 v[46:49], v[166:169], v[198:201], v[46:49]
	v_mfma_f32_16x16x32_bf16 v[38:41], v[158:161], v[206:209], v[38:41]
	v_mfma_f32_16x16x32_bf16 v[30:33], v[166:169], v[206:209], v[30:33]
	v_mfma_f32_16x16x32_bf16 v[22:25], v[158:161], v[214:217], v[22:25]
	v_mfma_f32_16x16x32_bf16 v[14:17], v[166:169], v[214:217], v[14:17]
	s_setprio 0
	s_setprio 1
	v_mfma_f32_16x16x32_bf16 v[50:53], v[170:173], v[186:189], v[50:53]
	v_mfma_f32_16x16x32_bf16 v[42:45], v[178:181], v[186:189], v[42:45]
	v_mfma_f32_16x16x32_bf16 v[34:37], v[170:173], v[194:197], v[34:37]
	v_mfma_f32_16x16x32_bf16 v[26:29], v[178:181], v[194:197], v[26:29]
	v_mfma_f32_16x16x32_bf16 v[18:21], v[170:173], v[202:205], v[18:21]
	v_mfma_f32_16x16x32_bf16 v[10:13], v[178:181], v[202:205], v[10:13]
	v_mfma_f32_16x16x32_bf16 v[6:9], v[170:173], v[210:213], v[6:9]
	v_mfma_f32_16x16x32_bf16 v[2:5], v[178:181], v[210:213], v[2:5]
	v_mfma_f32_16x16x32_bf16 v[50:53], v[174:177], v[190:193], v[50:53]
	v_mfma_f32_16x16x32_bf16 v[42:45], v[182:185], v[190:193], v[42:45]
	v_mfma_f32_16x16x32_bf16 v[34:37], v[174:177], v[198:201], v[34:37]
	v_mfma_f32_16x16x32_bf16 v[26:29], v[182:185], v[198:201], v[26:29]
	v_mfma_f32_16x16x32_bf16 v[18:21], v[174:177], v[206:209], v[18:21]
	v_mfma_f32_16x16x32_bf16 v[10:13], v[182:185], v[206:209], v[10:13]
	v_mfma_f32_16x16x32_bf16 v[6:9], v[174:177], v[214:217], v[6:9]
	v_mfma_f32_16x16x32_bf16 v[2:5], v[182:185], v[214:217], v[2:5]
	s_setprio 0
	s_barrier
	s_add_i32 s65, 0, 0x18000
	v_add_u32_e32 v153, s65, v148
	s_add_i32 s66, 0, 0x1c000
	ds_read_b128 v[154:157], v153
	ds_read_b128 v[158:161], v153 offset:1024
	ds_read_b128 v[162:165], v153 offset:2048
	ds_read_b128 v[166:169], v153 offset:3072
	v_add_u32_e32 v153, s66, v148
	ds_read_b128 v[170:173], v153
	ds_read_b128 v[174:177], v153 offset:1024
	ds_read_b128 v[178:181], v153 offset:2048
	ds_read_b128 v[182:185], v153 offset:3072
	s_add_u32 s42, s42, 0x100000
	s_addc_u32 s43, s43, 0
	s_mov_b32 m0, s45
	v_lshl_add_u64 v[224:225], s[42:43], 0, v[130:131]
	ds_read_b128 v[186:189], v152 offset:32768
	ds_read_b128 v[190:193], v152 offset:33792
	ds_read_b128 v[194:197], v152 offset:34816
	ds_read_b128 v[198:201], v152 offset:35840
	ds_read_b128 v[202:205], v152 offset:36864
	ds_read_b128 v[206:209], v152 offset:37888
	ds_read_b128 v[210:213], v152 offset:38912
	ds_read_b128 v[214:217], v152 offset:39936
	global_load_lds_dwordx4 v[224:225], off
	v_lshl_add_u64 v[224:225], s[42:43], 0, v[134:135]
	s_mov_b32 m0, s46
	s_nop 0
	global_load_lds_dwordx4 v[224:225], off
	s_waitcnt vmcnt(8)
	s_waitcnt lgkmcnt(0)
	s_barrier
	s_setprio 1
	s_waitcnt lgkmcnt(0)
	v_mfma_f32_16x16x32_bf16 v[126:129], v[154:157], v[186:189], v[126:129]
	v_mfma_f32_16x16x32_bf16 v[122:125], v[162:165], v[186:189], v[122:125]
	v_mfma_f32_16x16x32_bf16 v[118:121], v[154:157], v[194:197], v[118:121]
	v_mfma_f32_16x16x32_bf16 v[110:113], v[162:165], v[194:197], v[110:113]
	v_mfma_f32_16x16x32_bf16 v[102:105], v[154:157], v[202:205], v[102:105]
	v_mfma_f32_16x16x32_bf16 v[94:97], v[162:165], v[202:205], v[94:97]
	v_mfma_f32_16x16x32_bf16 v[86:89], v[154:157], v[210:213], v[86:89]
	v_mfma_f32_16x16x32_bf16 v[78:81], v[162:165], v[210:213], v[78:81]
	v_mfma_f32_16x16x32_bf16 v[126:129], v[158:161], v[190:193], v[126:129]
	v_mfma_f32_16x16x32_bf16 v[122:125], v[166:169], v[190:193], v[122:125]
	v_mfma_f32_16x16x32_bf16 v[118:121], v[158:161], v[198:201], v[118:121]
	v_mfma_f32_16x16x32_bf16 v[110:113], v[166:169], v[198:201], v[110:113]
	v_mfma_f32_16x16x32_bf16 v[102:105], v[158:161], v[206:209], v[102:105]
	v_mfma_f32_16x16x32_bf16 v[94:97], v[166:169], v[206:209], v[94:97]
	v_mfma_f32_16x16x32_bf16 v[86:89], v[158:161], v[214:217], v[86:89]
	v_mfma_f32_16x16x32_bf16 v[78:81], v[166:169], v[214:217], v[78:81]
	s_setprio 0
	s_setprio 1
	v_mfma_f32_16x16x32_bf16 v[114:117], v[170:173], v[186:189], v[114:117]
	v_mfma_f32_16x16x32_bf16 v[106:109], v[178:181], v[186:189], v[106:109]
	v_mfma_f32_16x16x32_bf16 v[98:101], v[170:173], v[194:197], v[98:101]
	v_mfma_f32_16x16x32_bf16 v[90:93], v[178:181], v[194:197], v[90:93]
	v_mfma_f32_16x16x32_bf16 v[82:85], v[170:173], v[202:205], v[82:85]
	v_mfma_f32_16x16x32_bf16 v[74:77], v[178:181], v[202:205], v[74:77]
	v_mfma_f32_16x16x32_bf16 v[70:73], v[170:173], v[210:213], v[70:73]
	v_mfma_f32_16x16x32_bf16 v[66:69], v[178:181], v[210:213], v[66:69]
	v_mfma_f32_16x16x32_bf16 v[114:117], v[174:177], v[190:193], v[114:117]
	v_mfma_f32_16x16x32_bf16 v[106:109], v[182:185], v[190:193], v[106:109]
	v_mfma_f32_16x16x32_bf16 v[98:101], v[174:177], v[198:201], v[98:101]
	v_mfma_f32_16x16x32_bf16 v[90:93], v[182:185], v[198:201], v[90:93]
	v_mfma_f32_16x16x32_bf16 v[82:85], v[174:177], v[206:209], v[82:85]
	v_mfma_f32_16x16x32_bf16 v[74:77], v[182:185], v[206:209], v[74:77]
	v_mfma_f32_16x16x32_bf16 v[70:73], v[174:177], v[214:217], v[70:73]
	v_mfma_f32_16x16x32_bf16 v[66:69], v[182:185], v[214:217], v[66:69]
	s_setprio 0
	s_barrier
	s_add_i32 s42, s65, s15
	v_lshl_add_u64 v[146:147], v[146:147], 0, s[10:11]
	s_mov_b32 m0, s42
	ds_read_b128 v[186:189], v152 offset:49152
	ds_read_b128 v[190:193], v152 offset:50176
	ds_read_b128 v[194:197], v152 offset:51200
	ds_read_b128 v[198:201], v152 offset:52224
	ds_read_b128 v[202:205], v152 offset:53248
	ds_read_b128 v[206:209], v152 offset:54272
	ds_read_b128 v[210:213], v152 offset:55296
	ds_read_b128 v[214:217], v152 offset:56320
	global_load_lds_dwordx4 v[146:147], off
	s_add_i32 m0, s42, 0x2000
	s_add_u32 s40, s40, 0x100080
	v_lshl_add_u64 v[146:147], v[218:219], 0, s[10:11]
	s_addc_u32 s41, s41, 0
	s_add_i32 s42, s66, s15
	global_load_lds_dwordx4 v[146:147], off
	v_lshl_add_u64 v[146:147], s[40:41], 0, v[132:133]
	s_mov_b32 m0, s42
	s_nop 0
	global_load_lds_dwordx4 v[146:147], off
	v_lshl_add_u64 v[146:147], s[40:41], 0, v[136:137]
	s_add_i32 m0, s42, 0x2000
	s_nop 0
	global_load_lds_dwordx4 v[146:147], off
	v_lshl_add_u64 v[146:147], v[220:221], 0, s[10:11]
	s_mov_b32 m0, s48
	s_nop 0
	global_load_lds_dwordx4 v[146:147], off
	v_lshl_add_u64 v[146:147], v[222:223], 0, s[10:11]
	s_mov_b32 m0, s49
	s_nop 0
	global_load_lds_dwordx4 v[146:147], off
	s_waitcnt vmcnt(8)
	s_waitcnt lgkmcnt(0)
	s_barrier
	s_setprio 1
	s_waitcnt lgkmcnt(0)
	v_mfma_f32_16x16x32_bf16 v[62:65], v[154:157], v[186:189], v[62:65]
	v_mfma_f32_16x16x32_bf16 v[58:61], v[162:165], v[186:189], v[58:61]
	v_mfma_f32_16x16x32_bf16 v[54:57], v[154:157], v[194:197], v[54:57]
	v_mfma_f32_16x16x32_bf16 v[46:49], v[162:165], v[194:197], v[46:49]
	v_mfma_f32_16x16x32_bf16 v[38:41], v[154:157], v[202:205], v[38:41]
	v_mfma_f32_16x16x32_bf16 v[30:33], v[162:165], v[202:205], v[30:33]
	v_mfma_f32_16x16x32_bf16 v[22:25], v[154:157], v[210:213], v[22:25]
	v_mfma_f32_16x16x32_bf16 v[14:17], v[162:165], v[210:213], v[14:17]
	v_mfma_f32_16x16x32_bf16 v[62:65], v[158:161], v[190:193], v[62:65]
	v_mfma_f32_16x16x32_bf16 v[58:61], v[166:169], v[190:193], v[58:61]
	v_mfma_f32_16x16x32_bf16 v[54:57], v[158:161], v[198:201], v[54:57]
	v_mfma_f32_16x16x32_bf16 v[46:49], v[166:169], v[198:201], v[46:49]
	v_mfma_f32_16x16x32_bf16 v[38:41], v[158:161], v[206:209], v[38:41]
	v_mfma_f32_16x16x32_bf16 v[30:33], v[166:169], v[206:209], v[30:33]
	v_mfma_f32_16x16x32_bf16 v[22:25], v[158:161], v[214:217], v[22:25]
	v_mfma_f32_16x16x32_bf16 v[14:17], v[166:169], v[214:217], v[14:17]
	s_setprio 0
	s_setprio 1
	v_mfma_f32_16x16x32_bf16 v[50:53], v[170:173], v[186:189], v[50:53]
	v_mfma_f32_16x16x32_bf16 v[42:45], v[178:181], v[186:189], v[42:45]
	v_mfma_f32_16x16x32_bf16 v[34:37], v[170:173], v[194:197], v[34:37]
	v_mfma_f32_16x16x32_bf16 v[26:29], v[178:181], v[194:197], v[26:29]
	v_mfma_f32_16x16x32_bf16 v[18:21], v[170:173], v[202:205], v[18:21]
	v_mfma_f32_16x16x32_bf16 v[10:13], v[178:181], v[202:205], v[10:13]
	v_mfma_f32_16x16x32_bf16 v[6:9], v[170:173], v[210:213], v[6:9]
	v_mfma_f32_16x16x32_bf16 v[2:5], v[178:181], v[210:213], v[2:5]
	v_mfma_f32_16x16x32_bf16 v[50:53], v[174:177], v[190:193], v[50:53]
	v_mfma_f32_16x16x32_bf16 v[42:45], v[182:185], v[190:193], v[42:45]
	v_mfma_f32_16x16x32_bf16 v[34:37], v[174:177], v[198:201], v[34:37]
	v_mfma_f32_16x16x32_bf16 v[26:29], v[182:185], v[198:201], v[26:29]
	v_mfma_f32_16x16x32_bf16 v[18:21], v[174:177], v[206:209], v[18:21]
	v_mfma_f32_16x16x32_bf16 v[10:13], v[182:185], v[206:209], v[10:13]
	v_mfma_f32_16x16x32_bf16 v[6:9], v[174:177], v[214:217], v[6:9]
	v_mfma_f32_16x16x32_bf16 v[2:5], v[182:185], v[214:217], v[2:5]
	s_setprio 0
	s_barrier
	ds_read_b128 v[154:157], v150
	ds_read_b128 v[158:161], v150 offset:1024
	ds_read_b128 v[162:165], v150 offset:2048
	ds_read_b128 v[166:169], v150 offset:3072
	ds_read_b128 v[170:173], v151
	ds_read_b128 v[174:177], v151 offset:1024
	ds_read_b128 v[178:181], v151 offset:2048
	ds_read_b128 v[182:185], v151 offset:3072
	s_add_i32 s64, s64, 2
	s_add_u32 s36, s36, 0x100
	s_addc_u32 s37, s37, 0
	s_add_u32 s62, s62, 0x100
	s_addc_u32 s63, s63, 0
	s_cmp_gt_u32 s64, 61
	s_cbranch_scc0 .Lkrot_1211
	s_waitcnt lgkmcnt(0)
	s_and_b64 vcc, exec, s[12:13]
	s_cbranch_vccz .LBB0_1214
	s_barrier

.Lkrot_1337:
	s_add_u32 s26, s24, 0xfff00080
	s_addc_u32 s27, s25, -1
	s_cmp_eq_u32 s53, 60
	s_cselect_b32 s29, s17, s27
	s_cselect_b32 s28, s49, s26
	s_cselect_b32 s27, s13, s52
	s_cselect_b32 s26, s50, s51
	v_lshl_add_u64 v[146:147], s[24:25], 0, v[138:139]
	s_add_i32 m0, s23, 0xc000
	ds_read_b128 v[186:189], v153
	ds_read_b128 v[190:193], v153 offset:1024
	ds_read_b128 v[194:197], v153 offset:2048
	ds_read_b128 v[198:201], v153 offset:3072
	ds_read_b128 v[202:205], v153 offset:4096
	ds_read_b128 v[206:209], v153 offset:5120
	ds_read_b128 v[210:213], v153 offset:6144
	ds_read_b128 v[214:217], v153 offset:7168
	global_load_lds_dwordx4 v[146:147], off
	v_lshl_add_u64 v[146:147], s[24:25], 0, v[140:141]
	s_add_i32 m0, s23, 0xe000
	s_nop 0
	global_load_lds_dwordx4 v[146:147], off
	s_waitcnt vmcnt(8)
	s_waitcnt lgkmcnt(0)
	s_barrier
	s_setprio 1
	s_waitcnt lgkmcnt(0)
	v_mfma_f32_16x16x32_bf16 v[126:129], v[154:157], v[186:189], v[126:129]
	v_mfma_f32_16x16x32_bf16 v[122:125], v[162:165], v[186:189], v[122:125]
	v_mfma_f32_16x16x32_bf16 v[110:113], v[154:157], v[194:197], v[110:113]
	v_mfma_f32_16x16x32_bf16 v[106:109], v[162:165], v[194:197], v[106:109]
	v_mfma_f32_16x16x32_bf16 v[94:97], v[154:157], v[202:205], v[94:97]
	v_mfma_f32_16x16x32_bf16 v[90:93], v[162:165], v[202:205], v[90:93]
	v_mfma_f32_16x16x32_bf16 v[78:81], v[154:157], v[210:213], v[78:81]
	v_mfma_f32_16x16x32_bf16 v[74:77], v[162:165], v[210:213], v[74:77]
	v_mfma_f32_16x16x32_bf16 v[126:129], v[158:161], v[190:193], v[126:129]
	v_mfma_f32_16x16x32_bf16 v[122:125], v[166:169], v[190:193], v[122:125]
	v_mfma_f32_16x16x32_bf16 v[110:113], v[158:161], v[198:201], v[110:113]
	v_mfma_f32_16x16x32_bf16 v[106:109], v[166:169], v[198:201], v[106:109]
	v_mfma_f32_16x16x32_bf16 v[94:97], v[158:161], v[206:209], v[94:97]
	v_mfma_f32_16x16x32_bf16 v[90:93], v[166:169], v[206:209], v[90:93]
	v_mfma_f32_16x16x32_bf16 v[78:81], v[158:161], v[214:217], v[78:81]
	v_mfma_f32_16x16x32_bf16 v[74:77], v[166:169], v[214:217], v[74:77]
	s_setprio 0
	s_setprio 1
	v_mfma_f32_16x16x32_bf16 v[118:121], v[170:173], v[186:189], v[118:121]
	v_mfma_f32_16x16x32_bf16 v[114:117], v[178:181], v[186:189], v[114:117]
	v_mfma_f32_16x16x32_bf16 v[102:105], v[170:173], v[194:197], v[102:105]
	v_mfma_f32_16x16x32_bf16 v[98:101], v[178:181], v[194:197], v[98:101]
	v_mfma_f32_16x16x32_bf16 v[86:89], v[170:173], v[202:205], v[86:89]
	v_mfma_f32_16x16x32_bf16 v[82:85], v[178:181], v[202:205], v[82:85]
	v_mfma_f32_16x16x32_bf16 v[70:73], v[170:173], v[210:213], v[70:73]
	v_mfma_f32_16x16x32_bf16 v[66:69], v[178:181], v[210:213], v[66:69]
	v_mfma_f32_16x16x32_bf16 v[118:121], v[174:177], v[190:193], v[118:121]
	v_mfma_f32_16x16x32_bf16 v[114:117], v[182:185], v[190:193], v[114:117]
	v_mfma_f32_16x16x32_bf16 v[102:105], v[174:177], v[198:201], v[102:105]
	v_mfma_f32_16x16x32_bf16 v[98:101], v[182:185], v[198:201], v[98:101]
	v_mfma_f32_16x16x32_bf16 v[86:89], v[174:177], v[206:209], v[86:89]
	v_mfma_f32_16x16x32_bf16 v[82:85], v[182:185], v[206:209], v[82:85]
	v_mfma_f32_16x16x32_bf16 v[70:73], v[174:177], v[214:217], v[70:73]
	v_mfma_f32_16x16x32_bf16 v[66:69], v[182:185], v[214:217], v[66:69]
	s_setprio 0
	s_barrier
	s_add_i32 s54, s45, s15
	v_lshl_add_u64 v[146:147], s[26:27], 0, v[134:135]
	s_mov_b32 m0, s54
	ds_read_b128 v[186:189], v153 offset:16384
	ds_read_b128 v[190:193], v153 offset:17408
	ds_read_b128 v[194:197], v153 offset:18432
	ds_read_b128 v[198:201], v153 offset:19456
	ds_read_b128 v[202:205], v153 offset:20480
	ds_read_b128 v[206:209], v153 offset:21504
	ds_read_b128 v[210:213], v153 offset:22528
	ds_read_b128 v[214:217], v153 offset:23552
	global_load_lds_dwordx4 v[146:147], off
	s_add_i32 m0, s54, 0x2000
	s_add_u32 s54, s26, 0x100000
	v_lshl_add_u64 v[218:219], s[26:27], 0, v[130:131]
	s_addc_u32 s55, s27, 0
	s_add_i32 s56, s46, s15
	global_load_lds_dwordx4 v[218:219], off
	v_lshl_add_u64 v[220:221], s[54:55], 0, v[134:135]
	s_mov_b32 m0, s56
	v_lshl_add_u64 v[222:223], s[28:29], 0, v[132:133]
	global_load_lds_dwordx4 v[220:221], off
	v_lshl_add_u64 v[220:221], s[54:55], 0, v[130:131]
	s_add_i32 m0, s56, 0x2000
	s_nop 0
	global_load_lds_dwordx4 v[220:221], off
	v_lshl_add_u64 v[220:221], s[28:29], 0, v[136:137]
	s_mov_b32 m0, s23
	s_nop 0
	global_load_lds_dwordx4 v[220:221], off
	s_mov_b32 m0, s36
	s_nop 0
	global_load_lds_dwordx4 v[222:223], off
	s_waitcnt vmcnt(8)
	s_waitcnt lgkmcnt(0)
	s_barrier
	s_setprio 1
	s_waitcnt lgkmcnt(0)
	v_mfma_f32_16x16x32_bf16 v[62:65], v[154:157], v[186:189], v[62:65]
	v_mfma_f32_16x16x32_bf16 v[58:61], v[162:165], v[186:189], v[58:61]
	v_mfma_f32_16x16x32_bf16 v[46:49], v[154:157], v[194:197], v[46:49]
	v_mfma_f32_16x16x32_bf16 v[42:45], v[162:165], v[194:197], v[42:45]
	v_mfma_f32_16x16x32_bf16 v[30:33], v[154:157], v[202:205], v[30:33]
	v_mfma_f32_16x16x32_bf16 v[26:29], v[162:165], v[202:205], v[26:29]
	v_mfma_f32_16x16x32_bf16 v[14:17], v[154:157], v[210:213], v[14:17]
	v_mfma_f32_16x16x32_bf16 v[10:13], v[162:165], v[210:213], v[10:13]
	v_mfma_f32_16x16x32_bf16 v[62:65], v[158:161], v[190:193], v[62:65]
	v_mfma_f32_16x16x32_bf16 v[58:61], v[166:169], v[190:193], v[58:61]
	v_mfma_f32_16x16x32_bf16 v[46:49], v[158:161], v[198:201], v[46:49]
	v_mfma_f32_16x16x32_bf16 v[42:45], v[166:169], v[198:201], v[42:45]
	v_mfma_f32_16x16x32_bf16 v[30:33], v[158:161], v[206:209], v[30:33]
	v_mfma_f32_16x16x32_bf16 v[26:29], v[166:169], v[206:209], v[26:29]
	v_mfma_f32_16x16x32_bf16 v[14:17], v[158:161], v[214:217], v[14:17]
	v_mfma_f32_16x16x32_bf16 v[10:13], v[166:169], v[214:217], v[10:13]
	s_setprio 0
	s_setprio 1
	v_mfma_f32_16x16x32_bf16 v[54:57], v[170:173], v[186:189], v[54:57]
	v_mfma_f32_16x16x32_bf16 v[50:53], v[178:181], v[186:189], v[50:53]
	v_mfma_f32_16x16x32_bf16 v[38:41], v[170:173], v[194:197], v[38:41]
	v_mfma_f32_16x16x32_bf16 v[34:37], v[178:181], v[194:197], v[34:37]
	v_mfma_f32_16x16x32_bf16 v[22:25], v[170:173], v[202:205], v[22:25]
	v_mfma_f32_16x16x32_bf16 v[18:21], v[178:181], v[202:205], v[18:21]
	v_mfma_f32_16x16x32_bf16 v[6:9], v[170:173], v[210:213], v[6:9]
	v_mfma_f32_16x16x32_bf16 v[2:5], v[178:181], v[210:213], v[2:5]
	v_mfma_f32_16x16x32_bf16 v[54:57], v[174:177], v[190:193], v[54:57]
	v_mfma_f32_16x16x32_bf16 v[50:53], v[182:185], v[190:193], v[50:53]
	v_mfma_f32_16x16x32_bf16 v[38:41], v[174:177], v[198:201], v[38:41]
	v_mfma_f32_16x16x32_bf16 v[34:37], v[182:185], v[198:201], v[34:37]
	v_mfma_f32_16x16x32_bf16 v[22:25], v[174:177], v[206:209], v[22:25]
	v_mfma_f32_16x16x32_bf16 v[18:21], v[182:185], v[206:209], v[18:21]
	v_mfma_f32_16x16x32_bf16 v[6:9], v[174:177], v[214:217], v[6:9]
	v_mfma_f32_16x16x32_bf16 v[2:5], v[182:185], v[214:217], v[2:5]
	s_setprio 0
	s_barrier
	s_add_i32 s54, 0, 0x18000
	s_add_i32 s55, 0, 0x1c000
	v_add_u32_e32 v166, s54, v149
	v_add_u32_e32 v182, s55, v149
	ds_read_b128 v[154:157], v166
	ds_read_b128 v[158:161], v166 offset:1024
	ds_read_b128 v[162:165], v166 offset:2048
	ds_read_b128 v[166:169], v166 offset:3072
	ds_read_b128 v[170:173], v182
	ds_read_b128 v[174:177], v182 offset:1024
	ds_read_b128 v[178:181], v182 offset:2048
	ds_read_b128 v[182:185], v182 offset:3072
	s_add_u32 s28, s28, 0x100000
	s_addc_u32 s29, s29, 0
	s_mov_b32 m0, s37
	v_lshl_add_u64 v[224:225], s[28:29], 0, v[136:137]
	ds_read_b128 v[186:189], v153 offset:32768
	ds_read_b128 v[190:193], v153 offset:33792
	ds_read_b128 v[194:197], v153 offset:34816
	ds_read_b128 v[198:201], v153 offset:35840
	ds_read_b128 v[202:205], v153 offset:36864
	ds_read_b128 v[206:209], v153 offset:37888
	ds_read_b128 v[210:213], v153 offset:38912
	ds_read_b128 v[214:217], v153 offset:39936
	global_load_lds_dwordx4 v[224:225], off
	v_lshl_add_u64 v[224:225], s[28:29], 0, v[132:133]
	s_mov_b32 m0, s40
	s_nop 0
	global_load_lds_dwordx4 v[224:225], off
	s_waitcnt vmcnt(8)
	s_waitcnt lgkmcnt(0)
	s_barrier
	s_setprio 1
	s_waitcnt lgkmcnt(0)
	v_mfma_f32_16x16x32_bf16 v[126:129], v[154:157], v[186:189], v[126:129]
	v_mfma_f32_16x16x32_bf16 v[122:125], v[162:165], v[186:189], v[122:125]
	v_mfma_f32_16x16x32_bf16 v[110:113], v[154:157], v[194:197], v[110:113]
	v_mfma_f32_16x16x32_bf16 v[106:109], v[162:165], v[194:197], v[106:109]
	v_mfma_f32_16x16x32_bf16 v[94:97], v[154:157], v[202:205], v[94:97]
	v_mfma_f32_16x16x32_bf16 v[90:93], v[162:165], v[202:205], v[90:93]
	v_mfma_f32_16x16x32_bf16 v[78:81], v[154:157], v[210:213], v[78:81]
	v_mfma_f32_16x16x32_bf16 v[74:77], v[162:165], v[210:213], v[74:77]
	v_mfma_f32_16x16x32_bf16 v[126:129], v[158:161], v[190:193], v[126:129]
	v_mfma_f32_16x16x32_bf16 v[122:125], v[166:169], v[190:193], v[122:125]
	v_mfma_f32_16x16x32_bf16 v[110:113], v[158:161], v[198:201], v[110:113]
	v_mfma_f32_16x16x32_bf16 v[106:109], v[166:169], v[198:201], v[106:109]
	v_mfma_f32_16x16x32_bf16 v[94:97], v[158:161], v[206:209], v[94:97]
	v_mfma_f32_16x16x32_bf16 v[90:93], v[166:169], v[206:209], v[90:93]
	v_mfma_f32_16x16x32_bf16 v[78:81], v[158:161], v[214:217], v[78:81]
	v_mfma_f32_16x16x32_bf16 v[74:77], v[166:169], v[214:217], v[74:77]
	s_setprio 0
	s_setprio 1
	v_mfma_f32_16x16x32_bf16 v[118:121], v[170:173], v[186:189], v[118:121]
	v_mfma_f32_16x16x32_bf16 v[114:117], v[178:181], v[186:189], v[114:117]
	v_mfma_f32_16x16x32_bf16 v[102:105], v[170:173], v[194:197], v[102:105]
	v_mfma_f32_16x16x32_bf16 v[98:101], v[178:181], v[194:197], v[98:101]
	v_mfma_f32_16x16x32_bf16 v[86:89], v[170:173], v[202:205], v[86:89]
	v_mfma_f32_16x16x32_bf16 v[82:85], v[178:181], v[202:205], v[82:85]
	v_mfma_f32_16x16x32_bf16 v[70:73], v[170:173], v[210:213], v[70:73]
	v_mfma_f32_16x16x32_bf16 v[66:69], v[178:181], v[210:213], v[66:69]
	v_mfma_f32_16x16x32_bf16 v[118:121], v[174:177], v[190:193], v[118:121]
	v_mfma_f32_16x16x32_bf16 v[114:117], v[182:185], v[190:193], v[114:117]
	v_mfma_f32_16x16x32_bf16 v[102:105], v[174:177], v[198:201], v[102:105]
	v_mfma_f32_16x16x32_bf16 v[98:101], v[182:185], v[198:201], v[98:101]
	v_mfma_f32_16x16x32_bf16 v[86:89], v[174:177], v[206:209], v[86:89]
	v_mfma_f32_16x16x32_bf16 v[82:85], v[182:185], v[206:209], v[82:85]
	v_mfma_f32_16x16x32_bf16 v[70:73], v[174:177], v[214:217], v[70:73]
	v_mfma_f32_16x16x32_bf16 v[66:69], v[182:185], v[214:217], v[66:69]
	s_setprio 0
	s_barrier
	s_add_i32 s28, s54, s15
	v_lshl_add_u64 v[146:147], v[146:147], 0, s[8:9]
	s_mov_b32 m0, s28
	ds_read_b128 v[186:189], v153 offset:49152
	ds_read_b128 v[190:193], v153 offset:50176
	ds_read_b128 v[194:197], v153 offset:51200
	ds_read_b128 v[198:201], v153 offset:52224
	ds_read_b128 v[202:205], v153 offset:53248
	ds_read_b128 v[206:209], v153 offset:54272
	ds_read_b128 v[210:213], v153 offset:55296
	ds_read_b128 v[214:217], v153 offset:56320
	global_load_lds_dwordx4 v[146:147], off
	s_add_i32 m0, s28, 0x2000
	s_add_u32 s26, s26, 0x100080
	v_lshl_add_u64 v[146:147], v[218:219], 0, s[8:9]
	s_addc_u32 s27, s27, 0
	s_add_i32 s28, s55, s15
	global_load_lds_dwordx4 v[146:147], off
	v_lshl_add_u64 v[146:147], s[26:27], 0, v[134:135]
	s_mov_b32 m0, s28
	s_nop 0
	global_load_lds_dwordx4 v[146:147], off
	v_lshl_add_u64 v[146:147], s[26:27], 0, v[130:131]
	s_add_i32 m0, s28, 0x2000
	s_nop 0
	global_load_lds_dwordx4 v[146:147], off
	v_lshl_add_u64 v[146:147], v[220:221], 0, s[8:9]
	s_mov_b32 m0, s42
	s_nop 0
	global_load_lds_dwordx4 v[146:147], off
	v_lshl_add_u64 v[146:147], v[222:223], 0, s[8:9]
	s_mov_b32 m0, s43
	s_nop 0
	global_load_lds_dwordx4 v[146:147], off
	s_waitcnt vmcnt(8)
	s_waitcnt lgkmcnt(0)
	s_barrier
	s_setprio 1
	s_waitcnt lgkmcnt(0)
	v_mfma_f32_16x16x32_bf16 v[62:65], v[154:157], v[186:189], v[62:65]
	v_mfma_f32_16x16x32_bf16 v[58:61], v[162:165], v[186:189], v[58:61]
	v_mfma_f32_16x16x32_bf16 v[46:49], v[154:157], v[194:197], v[46:49]
	v_mfma_f32_16x16x32_bf16 v[42:45], v[162:165], v[194:197], v[42:45]
	v_mfma_f32_16x16x32_bf16 v[30:33], v[154:157], v[202:205], v[30:33]
	v_mfma_f32_16x16x32_bf16 v[26:29], v[162:165], v[202:205], v[26:29]
	v_mfma_f32_16x16x32_bf16 v[14:17], v[154:157], v[210:213], v[14:17]
	v_mfma_f32_16x16x32_bf16 v[10:13], v[162:165], v[210:213], v[10:13]
	v_mfma_f32_16x16x32_bf16 v[62:65], v[158:161], v[190:193], v[62:65]
	v_mfma_f32_16x16x32_bf16 v[58:61], v[166:169], v[190:193], v[58:61]
	v_mfma_f32_16x16x32_bf16 v[46:49], v[158:161], v[198:201], v[46:49]
	v_mfma_f32_16x16x32_bf16 v[42:45], v[166:169], v[198:201], v[42:45]
	v_mfma_f32_16x16x32_bf16 v[30:33], v[158:161], v[206:209], v[30:33]
	v_mfma_f32_16x16x32_bf16 v[26:29], v[166:169], v[206:209], v[26:29]
	v_mfma_f32_16x16x32_bf16 v[14:17], v[158:161], v[214:217], v[14:17]
	v_mfma_f32_16x16x32_bf16 v[10:13], v[166:169], v[214:217], v[10:13]
	s_setprio 0
	s_setprio 1
	v_mfma_f32_16x16x32_bf16 v[54:57], v[170:173], v[186:189], v[54:57]
	v_mfma_f32_16x16x32_bf16 v[50:53], v[178:181], v[186:189], v[50:53]
	v_mfma_f32_16x16x32_bf16 v[38:41], v[170:173], v[194:197], v[38:41]
	v_mfma_f32_16x16x32_bf16 v[34:37], v[178:181], v[194:197], v[34:37]
	v_mfma_f32_16x16x32_bf16 v[22:25], v[170:173], v[202:205], v[22:25]
	v_mfma_f32_16x16x32_bf16 v[18:21], v[178:181], v[202:205], v[18:21]
	v_mfma_f32_16x16x32_bf16 v[6:9], v[170:173], v[210:213], v[6:9]
	v_mfma_f32_16x16x32_bf16 v[2:5], v[178:181], v[210:213], v[2:5]
	v_mfma_f32_16x16x32_bf16 v[54:57], v[174:177], v[190:193], v[54:57]
	v_mfma_f32_16x16x32_bf16 v[50:53], v[182:185], v[190:193], v[50:53]
	v_mfma_f32_16x16x32_bf16 v[38:41], v[174:177], v[198:201], v[38:41]
	v_mfma_f32_16x16x32_bf16 v[34:37], v[182:185], v[198:201], v[34:37]
	v_mfma_f32_16x16x32_bf16 v[22:25], v[174:177], v[206:209], v[22:25]
	v_mfma_f32_16x16x32_bf16 v[18:21], v[182:185], v[206:209], v[18:21]
	v_mfma_f32_16x16x32_bf16 v[6:9], v[174:177], v[214:217], v[6:9]
	v_mfma_f32_16x16x32_bf16 v[2:5], v[182:185], v[214:217], v[2:5]
	s_setprio 0
	s_barrier
	ds_read_b128 v[154:157], v151
	ds_read_b128 v[158:161], v151 offset:1024
	ds_read_b128 v[162:165], v151 offset:2048
	ds_read_b128 v[166:169], v151 offset:3072
	ds_read_b128 v[170:173], v152
	ds_read_b128 v[174:177], v152 offset:1024
	ds_read_b128 v[178:181], v152 offset:2048
	ds_read_b128 v[182:185], v152 offset:3072
	s_add_i32 s53, s53, 2
	s_add_u32 s24, s24, 0x100
	s_addc_u32 s25, s25, 0
	s_add_u32 s51, s51, 0x100
	s_addc_u32 s52, s52, 0
	s_cmp_gt_u32 s53, 61
	s_cbranch_scc0 .Lkrot_1337
	s_waitcnt lgkmcnt(0)
	s_and_b64 vcc, exec, s[10:11]
	s_cbranch_vccz .LBB0_1340
	s_barrier

.Lkrot_1434:
	s_add_u32 s30, s28, 0x100
	s_addc_u32 s31, s29, 0
	s_cmpk_eq_i32 s66, 0xa8
	s_cselect_b32 s41, s5, s31
	s_cselect_b32 s40, s4, s30
	s_cselect_b32 s37, s27, s65
	s_cselect_b32 s36, s26, s64
	v_lshl_add_u64 v[146:147], s[28:29], 0, v[138:139]
	s_add_i32 m0, s15, 0xc000
	ds_read_b128 v[186:189], v152
	ds_read_b128 v[190:193], v152 offset:1024
	ds_read_b128 v[194:197], v152 offset:2048
	ds_read_b128 v[198:201], v152 offset:3072
	ds_read_b128 v[202:205], v152 offset:4096
	ds_read_b128 v[206:209], v152 offset:5120
	ds_read_b128 v[210:213], v152 offset:6144
	ds_read_b128 v[214:217], v152 offset:7168
	global_load_lds_dwordx4 v[146:147], off
	v_lshl_add_u64 v[146:147], s[28:29], 0, v[140:141]
	s_add_i32 m0, s15, 0xe000
	s_nop 0
	global_load_lds_dwordx4 v[146:147], off
	s_waitcnt vmcnt(8)
	s_waitcnt lgkmcnt(0)
	s_barrier
	s_setprio 1
	s_waitcnt lgkmcnt(0)
	v_mfma_f32_16x16x32_bf16 v[126:129], v[154:157], v[186:189], v[126:129]
	v_mfma_f32_16x16x32_bf16 v[122:125], v[162:165], v[186:189], v[122:125]
	v_mfma_f32_16x16x32_bf16 v[118:121], v[154:157], v[194:197], v[118:121]
	v_mfma_f32_16x16x32_bf16 v[110:113], v[162:165], v[194:197], v[110:113]
	v_mfma_f32_16x16x32_bf16 v[102:105], v[154:157], v[202:205], v[102:105]
	v_mfma_f32_16x16x32_bf16 v[94:97], v[162:165], v[202:205], v[94:97]
	v_mfma_f32_16x16x32_bf16 v[86:89], v[154:157], v[210:213], v[86:89]
	v_mfma_f32_16x16x32_bf16 v[78:81], v[162:165], v[210:213], v[78:81]
	v_mfma_f32_16x16x32_bf16 v[126:129], v[158:161], v[190:193], v[126:129]
	v_mfma_f32_16x16x32_bf16 v[122:125], v[166:169], v[190:193], v[122:125]
	v_mfma_f32_16x16x32_bf16 v[118:121], v[158:161], v[198:201], v[118:121]
	v_mfma_f32_16x16x32_bf16 v[110:113], v[166:169], v[198:201], v[110:113]
	v_mfma_f32_16x16x32_bf16 v[102:105], v[158:161], v[206:209], v[102:105]
	v_mfma_f32_16x16x32_bf16 v[94:97], v[166:169], v[206:209], v[94:97]
	v_mfma_f32_16x16x32_bf16 v[86:89], v[158:161], v[214:217], v[86:89]
	v_mfma_f32_16x16x32_bf16 v[78:81], v[166:169], v[214:217], v[78:81]
	s_setprio 0
	s_setprio 1
	v_mfma_f32_16x16x32_bf16 v[114:117], v[170:173], v[186:189], v[114:117]
	v_mfma_f32_16x16x32_bf16 v[106:109], v[178:181], v[186:189], v[106:109]
	v_mfma_f32_16x16x32_bf16 v[98:101], v[170:173], v[194:197], v[98:101]
	v_mfma_f32_16x16x32_bf16 v[90:93], v[178:181], v[194:197], v[90:93]
	v_mfma_f32_16x16x32_bf16 v[82:85], v[170:173], v[202:205], v[82:85]
	v_mfma_f32_16x16x32_bf16 v[74:77], v[178:181], v[202:205], v[74:77]
	v_mfma_f32_16x16x32_bf16 v[70:73], v[170:173], v[210:213], v[70:73]
	v_mfma_f32_16x16x32_bf16 v[66:69], v[178:181], v[210:213], v[66:69]
	v_mfma_f32_16x16x32_bf16 v[114:117], v[174:177], v[190:193], v[114:117]
	v_mfma_f32_16x16x32_bf16 v[106:109], v[182:185], v[190:193], v[106:109]
	v_mfma_f32_16x16x32_bf16 v[98:101], v[174:177], v[198:201], v[98:101]
	v_mfma_f32_16x16x32_bf16 v[90:93], v[182:185], v[198:201], v[90:93]
	v_mfma_f32_16x16x32_bf16 v[82:85], v[174:177], v[206:209], v[82:85]
	v_mfma_f32_16x16x32_bf16 v[74:77], v[182:185], v[206:209], v[74:77]
	v_mfma_f32_16x16x32_bf16 v[70:73], v[174:177], v[214:217], v[70:73]
	v_mfma_f32_16x16x32_bf16 v[66:69], v[182:185], v[214:217], v[66:69]
	s_setprio 0
	s_barrier
	s_add_i32 s28, s52, s3
	v_lshl_add_u64 v[146:147], s[36:37], 0, v[132:133]
	s_mov_b32 m0, s28
	ds_read_b128 v[186:189], v152 offset:16384
	ds_read_b128 v[190:193], v152 offset:17408
	ds_read_b128 v[194:197], v152 offset:18432
	ds_read_b128 v[198:201], v152 offset:19456
	ds_read_b128 v[202:205], v152 offset:20480
	ds_read_b128 v[206:209], v152 offset:21504
	ds_read_b128 v[210:213], v152 offset:22528
	ds_read_b128 v[214:217], v152 offset:23552
	global_load_lds_dwordx4 v[146:147], off
	s_add_i32 m0, s28, 0x2000
	s_add_u32 s28, s36, 0x2b0000
	v_lshl_add_u64 v[218:219], s[36:37], 0, v[136:137]
	s_addc_u32 s29, s37, 0
	s_add_i32 s67, s53, s3
	global_load_lds_dwordx4 v[218:219], off
	v_lshl_add_u64 v[220:221], s[28:29], 0, v[132:133]
	s_mov_b32 m0, s67
	v_lshl_add_u64 v[222:223], s[40:41], 0, v[134:135]
	global_load_lds_dwordx4 v[220:221], off
	v_lshl_add_u64 v[220:221], s[28:29], 0, v[136:137]
	s_add_i32 m0, s67, 0x2000
	s_nop 0
	global_load_lds_dwordx4 v[220:221], off
	v_lshl_add_u64 v[220:221], s[40:41], 0, v[130:131]
	s_mov_b32 m0, s15
	s_nop 0
	global_load_lds_dwordx4 v[220:221], off
	s_mov_b32 m0, s42
	s_nop 0
	global_load_lds_dwordx4 v[222:223], off
	s_waitcnt vmcnt(8)
	s_waitcnt lgkmcnt(0)
	s_barrier
	s_setprio 1
	s_waitcnt lgkmcnt(0)
	v_mfma_f32_16x16x32_bf16 v[62:65], v[154:157], v[186:189], v[62:65]
	v_mfma_f32_16x16x32_bf16 v[58:61], v[162:165], v[186:189], v[58:61]
	v_mfma_f32_16x16x32_bf16 v[54:57], v[154:157], v[194:197], v[54:57]
	v_mfma_f32_16x16x32_bf16 v[46:49], v[162:165], v[194:197], v[46:49]
	v_mfma_f32_16x16x32_bf16 v[38:41], v[154:157], v[202:205], v[38:41]
	v_mfma_f32_16x16x32_bf16 v[30:33], v[162:165], v[202:205], v[30:33]
	v_mfma_f32_16x16x32_bf16 v[22:25], v[154:157], v[210:213], v[22:25]
	v_mfma_f32_16x16x32_bf16 v[14:17], v[162:165], v[210:213], v[14:17]
	v_mfma_f32_16x16x32_bf16 v[62:65], v[158:161], v[190:193], v[62:65]
	v_mfma_f32_16x16x32_bf16 v[58:61], v[166:169], v[190:193], v[58:61]
	v_mfma_f32_16x16x32_bf16 v[54:57], v[158:161], v[198:201], v[54:57]
	v_mfma_f32_16x16x32_bf16 v[46:49], v[166:169], v[198:201], v[46:49]
	v_mfma_f32_16x16x32_bf16 v[38:41], v[158:161], v[206:209], v[38:41]
	v_mfma_f32_16x16x32_bf16 v[30:33], v[166:169], v[206:209], v[30:33]
	v_mfma_f32_16x16x32_bf16 v[22:25], v[158:161], v[214:217], v[22:25]
	v_mfma_f32_16x16x32_bf16 v[14:17], v[166:169], v[214:217], v[14:17]
	s_setprio 0
	s_setprio 1
	v_mfma_f32_16x16x32_bf16 v[50:53], v[170:173], v[186:189], v[50:53]
	v_mfma_f32_16x16x32_bf16 v[42:45], v[178:181], v[186:189], v[42:45]
	v_mfma_f32_16x16x32_bf16 v[34:37], v[170:173], v[194:197], v[34:37]
	v_mfma_f32_16x16x32_bf16 v[26:29], v[178:181], v[194:197], v[26:29]
	v_mfma_f32_16x16x32_bf16 v[18:21], v[170:173], v[202:205], v[18:21]
	v_mfma_f32_16x16x32_bf16 v[10:13], v[178:181], v[202:205], v[10:13]
	v_mfma_f32_16x16x32_bf16 v[6:9], v[170:173], v[210:213], v[6:9]
	v_mfma_f32_16x16x32_bf16 v[2:5], v[178:181], v[210:213], v[2:5]
	v_mfma_f32_16x16x32_bf16 v[50:53], v[174:177], v[190:193], v[50:53]
	v_mfma_f32_16x16x32_bf16 v[42:45], v[182:185], v[190:193], v[42:45]
	v_mfma_f32_16x16x32_bf16 v[34:37], v[174:177], v[198:201], v[34:37]
	v_mfma_f32_16x16x32_bf16 v[26:29], v[182:185], v[198:201], v[26:29]
	v_mfma_f32_16x16x32_bf16 v[18:21], v[174:177], v[206:209], v[18:21]
	v_mfma_f32_16x16x32_bf16 v[10:13], v[182:185], v[206:209], v[10:13]
	v_mfma_f32_16x16x32_bf16 v[6:9], v[174:177], v[214:217], v[6:9]
	v_mfma_f32_16x16x32_bf16 v[2:5], v[182:185], v[214:217], v[2:5]
	s_setprio 0
	s_barrier
	s_add_i32 s67, 0, 0x18000
	v_add_u32_e32 v153, s67, v148
	s_add_i32 s68, 0, 0x1c000
	ds_read_b128 v[154:157], v153
	ds_read_b128 v[158:161], v153 offset:1024
	ds_read_b128 v[162:165], v153 offset:2048
	ds_read_b128 v[166:169], v153 offset:3072
	v_add_u32_e32 v153, s68, v148
	ds_read_b128 v[170:173], v153
	ds_read_b128 v[174:177], v153 offset:1024
	ds_read_b128 v[178:181], v153 offset:2048
	ds_read_b128 v[182:185], v153 offset:3072
	s_add_u32 s28, s40, 0x2b0000
	s_addc_u32 s29, s41, 0
	s_mov_b32 m0, s43
	v_lshl_add_u64 v[224:225], s[28:29], 0, v[130:131]
	ds_read_b128 v[186:189], v152 offset:32768
	ds_read_b128 v[190:193], v152 offset:33792
	ds_read_b128 v[194:197], v152 offset:34816
	ds_read_b128 v[198:201], v152 offset:35840
	ds_read_b128 v[202:205], v152 offset:36864
	ds_read_b128 v[206:209], v152 offset:37888
	ds_read_b128 v[210:213], v152 offset:38912
	ds_read_b128 v[214:217], v152 offset:39936
	global_load_lds_dwordx4 v[224:225], off
	v_lshl_add_u64 v[224:225], s[28:29], 0, v[134:135]
	s_mov_b32 m0, s44
	s_nop 0
	global_load_lds_dwordx4 v[224:225], off
	s_waitcnt vmcnt(8)
	s_waitcnt lgkmcnt(0)
	s_barrier
	s_setprio 1
	s_waitcnt lgkmcnt(0)
	v_mfma_f32_16x16x32_bf16 v[126:129], v[154:157], v[186:189], v[126:129]
	v_mfma_f32_16x16x32_bf16 v[122:125], v[162:165], v[186:189], v[122:125]
	v_mfma_f32_16x16x32_bf16 v[118:121], v[154:157], v[194:197], v[118:121]
	v_mfma_f32_16x16x32_bf16 v[110:113], v[162:165], v[194:197], v[110:113]
	v_mfma_f32_16x16x32_bf16 v[102:105], v[154:157], v[202:205], v[102:105]
	v_mfma_f32_16x16x32_bf16 v[94:97], v[162:165], v[202:205], v[94:97]
	v_mfma_f32_16x16x32_bf16 v[86:89], v[154:157], v[210:213], v[86:89]
	v_mfma_f32_16x16x32_bf16 v[78:81], v[162:165], v[210:213], v[78:81]
	v_mfma_f32_16x16x32_bf16 v[126:129], v[158:161], v[190:193], v[126:129]
	v_mfma_f32_16x16x32_bf16 v[122:125], v[166:169], v[190:193], v[122:125]
	v_mfma_f32_16x16x32_bf16 v[118:121], v[158:161], v[198:201], v[118:121]
	v_mfma_f32_16x16x32_bf16 v[110:113], v[166:169], v[198:201], v[110:113]
	v_mfma_f32_16x16x32_bf16 v[102:105], v[158:161], v[206:209], v[102:105]
	v_mfma_f32_16x16x32_bf16 v[94:97], v[166:169], v[206:209], v[94:97]
	v_mfma_f32_16x16x32_bf16 v[86:89], v[158:161], v[214:217], v[86:89]
	v_mfma_f32_16x16x32_bf16 v[78:81], v[166:169], v[214:217], v[78:81]
	s_setprio 0
	s_setprio 1
	v_mfma_f32_16x16x32_bf16 v[114:117], v[170:173], v[186:189], v[114:117]
	v_mfma_f32_16x16x32_bf16 v[106:109], v[178:181], v[186:189], v[106:109]
	v_mfma_f32_16x16x32_bf16 v[98:101], v[170:173], v[194:197], v[98:101]
	v_mfma_f32_16x16x32_bf16 v[90:93], v[178:181], v[194:197], v[90:93]
	v_mfma_f32_16x16x32_bf16 v[82:85], v[170:173], v[202:205], v[82:85]
	v_mfma_f32_16x16x32_bf16 v[74:77], v[178:181], v[202:205], v[74:77]
	v_mfma_f32_16x16x32_bf16 v[70:73], v[170:173], v[210:213], v[70:73]
	v_mfma_f32_16x16x32_bf16 v[66:69], v[178:181], v[210:213], v[66:69]
	v_mfma_f32_16x16x32_bf16 v[114:117], v[174:177], v[190:193], v[114:117]
	v_mfma_f32_16x16x32_bf16 v[106:109], v[182:185], v[190:193], v[106:109]
	v_mfma_f32_16x16x32_bf16 v[98:101], v[174:177], v[198:201], v[98:101]
	v_mfma_f32_16x16x32_bf16 v[90:93], v[182:185], v[198:201], v[90:93]
	v_mfma_f32_16x16x32_bf16 v[82:85], v[174:177], v[206:209], v[82:85]
	v_mfma_f32_16x16x32_bf16 v[74:77], v[182:185], v[206:209], v[74:77]
	v_mfma_f32_16x16x32_bf16 v[70:73], v[174:177], v[214:217], v[70:73]
	v_mfma_f32_16x16x32_bf16 v[66:69], v[182:185], v[214:217], v[66:69]
	s_setprio 0
	s_barrier
	s_add_i32 s28, s67, s3
	v_lshl_add_u64 v[146:147], v[146:147], 0, s[12:13]
	s_mov_b32 m0, s28
	ds_read_b128 v[186:189], v152 offset:49152
	ds_read_b128 v[190:193], v152 offset:50176
	ds_read_b128 v[194:197], v152 offset:51200
	ds_read_b128 v[198:201], v152 offset:52224
	ds_read_b128 v[202:205], v152 offset:53248
	ds_read_b128 v[206:209], v152 offset:54272
	ds_read_b128 v[210:213], v152 offset:55296
	ds_read_b128 v[214:217], v152 offset:56320
	global_load_lds_dwordx4 v[146:147], off
	s_add_i32 m0, s28, 0x2000
	s_add_u32 s28, s36, 0x2b0080
	v_lshl_add_u64 v[146:147], v[218:219], 0, s[12:13]
	s_addc_u32 s29, s37, 0
	s_add_i32 s36, s68, s3
	global_load_lds_dwordx4 v[146:147], off
	v_lshl_add_u64 v[146:147], s[28:29], 0, v[132:133]
	s_mov_b32 m0, s36
	s_nop 0
	global_load_lds_dwordx4 v[146:147], off
	v_lshl_add_u64 v[146:147], s[28:29], 0, v[136:137]
	s_add_i32 m0, s36, 0x2000
	s_nop 0
	global_load_lds_dwordx4 v[146:147], off
	v_lshl_add_u64 v[146:147], v[220:221], 0, s[12:13]
	s_mov_b32 m0, s46
	s_nop 0
	global_load_lds_dwordx4 v[146:147], off
	v_lshl_add_u64 v[146:147], v[222:223], 0, s[12:13]
	s_mov_b32 m0, s47
	s_nop 0
	global_load_lds_dwordx4 v[146:147], off
	s_waitcnt vmcnt(8)
	s_waitcnt lgkmcnt(0)
	s_barrier
	s_setprio 1
	s_waitcnt lgkmcnt(0)
	v_mfma_f32_16x16x32_bf16 v[62:65], v[154:157], v[186:189], v[62:65]
	v_mfma_f32_16x16x32_bf16 v[58:61], v[162:165], v[186:189], v[58:61]
	v_mfma_f32_16x16x32_bf16 v[54:57], v[154:157], v[194:197], v[54:57]
	v_mfma_f32_16x16x32_bf16 v[46:49], v[162:165], v[194:197], v[46:49]
	v_mfma_f32_16x16x32_bf16 v[38:41], v[154:157], v[202:205], v[38:41]
	v_mfma_f32_16x16x32_bf16 v[30:33], v[162:165], v[202:205], v[30:33]
	v_mfma_f32_16x16x32_bf16 v[22:25], v[154:157], v[210:213], v[22:25]
	v_mfma_f32_16x16x32_bf16 v[14:17], v[162:165], v[210:213], v[14:17]
	v_mfma_f32_16x16x32_bf16 v[62:65], v[158:161], v[190:193], v[62:65]
	v_mfma_f32_16x16x32_bf16 v[58:61], v[166:169], v[190:193], v[58:61]
	v_mfma_f32_16x16x32_bf16 v[54:57], v[158:161], v[198:201], v[54:57]
	v_mfma_f32_16x16x32_bf16 v[46:49], v[166:169], v[198:201], v[46:49]
	v_mfma_f32_16x16x32_bf16 v[38:41], v[158:161], v[206:209], v[38:41]
	v_mfma_f32_16x16x32_bf16 v[30:33], v[166:169], v[206:209], v[30:33]
	v_mfma_f32_16x16x32_bf16 v[22:25], v[158:161], v[214:217], v[22:25]
	v_mfma_f32_16x16x32_bf16 v[14:17], v[166:169], v[214:217], v[14:17]
	s_setprio 0
	s_setprio 1
	v_mfma_f32_16x16x32_bf16 v[50:53], v[170:173], v[186:189], v[50:53]
	v_mfma_f32_16x16x32_bf16 v[42:45], v[178:181], v[186:189], v[42:45]
	v_mfma_f32_16x16x32_bf16 v[34:37], v[170:173], v[194:197], v[34:37]
	v_mfma_f32_16x16x32_bf16 v[26:29], v[178:181], v[194:197], v[26:29]
	v_mfma_f32_16x16x32_bf16 v[18:21], v[170:173], v[202:205], v[18:21]
	v_mfma_f32_16x16x32_bf16 v[10:13], v[178:181], v[202:205], v[10:13]
	v_mfma_f32_16x16x32_bf16 v[6:9], v[170:173], v[210:213], v[6:9]
	v_mfma_f32_16x16x32_bf16 v[2:5], v[178:181], v[210:213], v[2:5]
	v_mfma_f32_16x16x32_bf16 v[50:53], v[174:177], v[190:193], v[50:53]
	v_mfma_f32_16x16x32_bf16 v[42:45], v[182:185], v[190:193], v[42:45]
	v_mfma_f32_16x16x32_bf16 v[34:37], v[174:177], v[198:201], v[34:37]
	v_mfma_f32_16x16x32_bf16 v[26:29], v[182:185], v[198:201], v[26:29]
	v_mfma_f32_16x16x32_bf16 v[18:21], v[174:177], v[206:209], v[18:21]
	v_mfma_f32_16x16x32_bf16 v[10:13], v[182:185], v[206:209], v[10:13]
	v_mfma_f32_16x16x32_bf16 v[6:9], v[174:177], v[214:217], v[6:9]
	v_mfma_f32_16x16x32_bf16 v[2:5], v[182:185], v[214:217], v[2:5]
	s_setprio 0
	s_barrier
	ds_read_b128 v[154:157], v150
	ds_read_b128 v[158:161], v150 offset:1024
	ds_read_b128 v[162:165], v150 offset:2048
	ds_read_b128 v[166:169], v150 offset:3072
	ds_read_b128 v[170:173], v151
	ds_read_b128 v[174:177], v151 offset:1024
	ds_read_b128 v[178:181], v151 offset:2048
	ds_read_b128 v[182:185], v151 offset:3072
	s_add_i32 s66, s66, 2
	s_add_u32 s64, s64, 0x100
	s_addc_u32 s65, s65, 0
	s_cmpk_gt_u32 s66, 0xa9
	s_mov_b64 s[28:29], s[30:31]
	s_cbranch_scc0 .Lkrot_1434
	s_waitcnt lgkmcnt(0)
	s_and_b64 vcc, exec, s[16:17]
	s_cbranch_vccz .LBB0_1437
	s_barrier
